# K-loop trims + accumulator clear moved out of the unit header into the first trip's two load segments (behind the issued ds_reads, first-trip flag), 64 v_mov_b64
# baseline (speedup 1.0000x reference)
.LBB0_269:
	s_ashr_i32 s25, s24, 31
	s_lshl_b64 s[26:27], s[24:25], 20
	s_add_u32 s26, s36, s26
	s_addc_u32 s27, s37, s27
	s_and_b64 s[28:29], s[6:7], exec
	s_cselect_b32 s2, s27, s31
	s_cselect_b32 s25, s26, s30
	s_ashr_i32 s23, s22, 31
	s_lshl_b64 s[28:29], s[22:23], 20
	s_add_u32 s28, s38, s28
	s_addc_u32 s29, s39, s29
	s_and_b64 s[34:35], s[6:7], exec
	s_cselect_b32 s23, s29, s57
	s_cselect_b32 s54, s28, s56
	s_ashr_i32 s1, s0, 31
	s_lshl_b64 s[34:35], s[0:1], 13
	s_add_u32 s1, s56, 0x100
	s_addc_u32 s55, s57, 0
	s_add_u32 s8, s30, 0x80080
	s_mov_b32 s98, 0
	s_waitcnt vmcnt(0)
	v_lshl_add_u64 v[66:67], v[168:169], 0, s[34:35]
	s_addc_u32 s9, s31, 0
	s_mov_b32 s56, -2
	s_branch .LBB0_271
.LBB0_270:
	s_add_u32 s34, s8, 0xfff80080
	s_addc_u32 s35, s9, -1
	s_and_b64 s[30:31], s[30:31], exec
	s_cselect_b32 s35, s2, s35
	s_cselect_b32 s34, s25, s34
	s_cselect_b32 s31, s23, s55
	s_cselect_b32 s30, s54, s1
	s_add_i32 s57, 0, 0x10000
	v_add_u32_e32 v72, s57, v181
	s_add_i32 s62, 0, 0x14000
	ds_read_b128 v[68:71], v72
	ds_read_b128 v[82:85], v72 offset:1024
	ds_read_b128 v[86:89], v72 offset:2048
	ds_read_b128 v[146:149], v72 offset:3072
	v_add_u32_e32 v72, s62, v181
	ds_read_b128 v[150:153], v72
	ds_read_b128 v[154:157], v72 offset:1024
	ds_read_b128 v[158:161], v72 offset:2048
	ds_read_b128 v[202:205], v72 offset:3072
	v_lshl_add_u64 v[72:73], s[8:9], 0, v[172:173]
	s_add_i32 m0, s41, 0xc000
	ds_read_b128 v[206:209], v199
	ds_read_b128 v[210:213], v199 offset:1024
	ds_read_b128 v[214:217], v199 offset:2048
	ds_read_b128 v[226:229], v199 offset:3072
	ds_read_b128 v[230:233], v199 offset:4096
	ds_read_b128 v[234:237], v199 offset:5120
	ds_read_b128 v[238:241], v199 offset:6144
	ds_read_b128 v[242:245], v199 offset:7168
	s_cmp_lg_u32 s98, 0
	s_cbranch_scc1 .Lzc_ph1_a
	v_mov_b64_e32 v[74:75], 0
	v_mov_b64_e32 v[76:77], 0
	v_mov_b64_e32 v[78:79], 0
	v_mov_b64_e32 v[80:81], 0
	v_mov_b64_e32 v[90:91], 0
	v_mov_b64_e32 v[92:93], 0
	v_mov_b64_e32 v[94:95], 0
	v_mov_b64_e32 v[96:97], 0
	v_mov_b64_e32 v[98:99], 0
	v_mov_b64_e32 v[100:101], 0
	v_mov_b64_e32 v[102:103], 0
	v_mov_b64_e32 v[104:105], 0
	v_mov_b64_e32 v[106:107], 0
	v_mov_b64_e32 v[108:109], 0
	v_mov_b64_e32 v[110:111], 0
	v_mov_b64_e32 v[112:113], 0
	v_mov_b64_e32 v[114:115], 0
	v_mov_b64_e32 v[116:117], 0
	v_mov_b64_e32 v[118:119], 0
	v_mov_b64_e32 v[120:121], 0
	v_mov_b64_e32 v[122:123], 0
	v_mov_b64_e32 v[124:125], 0
	v_mov_b64_e32 v[126:127], 0
	v_mov_b64_e32 v[128:129], 0
	v_mov_b64_e32 v[130:131], 0
	v_mov_b64_e32 v[132:133], 0
	v_mov_b64_e32 v[134:135], 0
	v_mov_b64_e32 v[136:137], 0
	v_mov_b64_e32 v[138:139], 0
	v_mov_b64_e32 v[140:141], 0
	v_mov_b64_e32 v[142:143], 0
	v_mov_b64_e32 v[144:145], 0
.Lzc_ph1_a:
	global_load_lds_dwordx4 v[72:73], off
	v_lshl_add_u64 v[72:73], s[8:9], 0, v[170:171]
	s_add_i32 m0, s41, 0xe000
	s_nop 0
	global_load_lds_dwordx4 v[72:73], off
	s_waitcnt vmcnt(8)
	s_waitcnt lgkmcnt(0)
	s_barrier
	s_setprio 1
	v_mfma_f32_16x16x32_bf16 v[142:145], v[68:71], v[206:209], v[142:145]
	v_mfma_f32_16x16x32_bf16 v[138:141], v[86:89], v[206:209], v[138:141]
	v_mfma_f32_16x16x32_bf16 v[126:129], v[68:71], v[214:217], v[126:129]
	v_mfma_f32_16x16x32_bf16 v[122:125], v[86:89], v[214:217], v[122:125]
	v_mfma_f32_16x16x32_bf16 v[110:113], v[68:71], v[230:233], v[110:113]
	v_mfma_f32_16x16x32_bf16 v[106:109], v[86:89], v[230:233], v[106:109]
	v_mfma_f32_16x16x32_bf16 v[94:97], v[68:71], v[238:241], v[94:97]
	v_mfma_f32_16x16x32_bf16 v[90:93], v[86:89], v[238:241], v[90:93]
	v_mfma_f32_16x16x32_bf16 v[142:145], v[82:85], v[210:213], v[142:145]
	v_mfma_f32_16x16x32_bf16 v[138:141], v[146:149], v[210:213], v[138:141]
	v_mfma_f32_16x16x32_bf16 v[126:129], v[82:85], v[226:229], v[126:129]
	v_mfma_f32_16x16x32_bf16 v[122:125], v[146:149], v[226:229], v[122:125]
	v_mfma_f32_16x16x32_bf16 v[110:113], v[82:85], v[234:237], v[110:113]
	v_mfma_f32_16x16x32_bf16 v[106:109], v[146:149], v[234:237], v[106:109]
	v_mfma_f32_16x16x32_bf16 v[94:97], v[82:85], v[242:245], v[94:97]
	v_mfma_f32_16x16x32_bf16 v[90:93], v[146:149], v[242:245], v[90:93]
	v_mfma_f32_16x16x32_bf16 v[134:137], v[150:153], v[206:209], v[134:137]
	v_mfma_f32_16x16x32_bf16 v[130:133], v[158:161], v[206:209], v[130:133]
	v_mfma_f32_16x16x32_bf16 v[118:121], v[150:153], v[214:217], v[118:121]
	v_mfma_f32_16x16x32_bf16 v[114:117], v[158:161], v[214:217], v[114:117]
	v_mfma_f32_16x16x32_bf16 v[102:105], v[150:153], v[230:233], v[102:105]
	v_mfma_f32_16x16x32_bf16 v[98:101], v[158:161], v[230:233], v[98:101]
	v_mfma_f32_16x16x32_bf16 v[78:81], v[150:153], v[238:241], v[78:81]
	v_mfma_f32_16x16x32_bf16 v[72:75], v[158:161], v[238:241], v[74:77]
	v_mfma_f32_16x16x32_bf16 v[134:137], v[154:157], v[210:213], v[134:137]
	v_mfma_f32_16x16x32_bf16 v[130:133], v[202:205], v[210:213], v[130:133]
	v_mfma_f32_16x16x32_bf16 v[118:121], v[154:157], v[226:229], v[118:121]
	v_mfma_f32_16x16x32_bf16 v[114:117], v[202:205], v[226:229], v[114:117]
	v_mfma_f32_16x16x32_bf16 v[102:105], v[154:157], v[234:237], v[102:105]
	v_mfma_f32_16x16x32_bf16 v[98:101], v[202:205], v[234:237], v[98:101]
	v_mfma_f32_16x16x32_bf16 v[78:81], v[154:157], v[242:245], v[78:81]
	v_mfma_f32_16x16x32_bf16 v[72:75], v[202:205], v[242:245], v[72:75]
	s_setprio 0
	s_barrier
	s_add_i32 s57, s57, s40
	v_lshl_add_u64 v[178:179], s[30:31], 0, v[0:1]
	s_mov_b32 m0, s57
	ds_read_b128 v[206:209], v199 offset:16384
	ds_read_b128 v[210:213], v199 offset:17408
	ds_read_b128 v[214:217], v199 offset:18432
	ds_read_b128 v[226:229], v199 offset:19456
	ds_read_b128 v[230:233], v199 offset:20480
	ds_read_b128 v[234:237], v199 offset:21504
	ds_read_b128 v[238:241], v199 offset:22528
	ds_read_b128 v[242:245], v199 offset:23552
	s_cmp_lg_u32 s98, 0
	s_cbranch_scc1 .Lzc_ph1_b
	v_mov_b64_e32 v[2:3], 0
	v_mov_b64_e32 v[4:5], 0
	v_mov_b64_e32 v[6:7], 0
	v_mov_b64_e32 v[8:9], 0
	v_mov_b64_e32 v[10:11], 0
	v_mov_b64_e32 v[12:13], 0
	v_mov_b64_e32 v[14:15], 0
	v_mov_b64_e32 v[16:17], 0
	v_mov_b64_e32 v[18:19], 0
	v_mov_b64_e32 v[20:21], 0
	v_mov_b64_e32 v[22:23], 0
	v_mov_b64_e32 v[24:25], 0
	v_mov_b64_e32 v[26:27], 0
	v_mov_b64_e32 v[28:29], 0
	v_mov_b64_e32 v[30:31], 0
	v_mov_b64_e32 v[32:33], 0
	v_mov_b64_e32 v[34:35], 0
	v_mov_b64_e32 v[36:37], 0
	v_mov_b64_e32 v[38:39], 0
	v_mov_b64_e32 v[40:41], 0
	v_mov_b64_e32 v[42:43], 0
	v_mov_b64_e32 v[44:45], 0
	v_mov_b64_e32 v[46:47], 0
	v_mov_b64_e32 v[48:49], 0
	v_mov_b64_e32 v[50:51], 0
	v_mov_b64_e32 v[52:53], 0
	v_mov_b64_e32 v[54:55], 0
	v_mov_b64_e32 v[56:57], 0
	v_mov_b64_e32 v[58:59], 0
	v_mov_b64_e32 v[60:61], 0
	v_mov_b64_e32 v[62:63], 0
	v_mov_b64_e32 v[64:65], 0
	s_mov_b32 s98, 1
.Lzc_ph1_b:
	global_load_lds_dwordx4 v[178:179], off
	s_add_i32 m0, s57, 0x2000
	s_add_u32 s60, s30, 0x80000
	v_lshl_add_u64 v[250:251], s[30:31], 0, v[162:163]
	s_addc_u32 s61, s31, 0
	s_add_i32 s57, s62, s40
	global_load_lds_dwordx4 v[250:251], off
	v_lshl_add_u64 v[76:77], s[60:61], 0, v[0:1]
	s_mov_b32 m0, s57
	v_lshl_add_u64 v[252:253], s[34:35], 0, v[166:167]
	global_load_lds_dwordx4 v[76:77], off
	v_lshl_add_u64 v[76:77], s[60:61], 0, v[162:163]
	s_add_i32 m0, s57, 0x2000
	v_lshl_add_u64 v[220:221], s[34:35], 0, v[164:165]
	global_load_lds_dwordx4 v[76:77], off
	s_mov_b32 m0, s41
	s_nop 0
	global_load_lds_dwordx4 v[252:253], off
	s_mov_b32 m0, s42
	s_nop 0
	global_load_lds_dwordx4 v[220:221], off
	s_waitcnt vmcnt(8)
	s_waitcnt lgkmcnt(0)
	s_barrier
	s_setprio 1
	v_mfma_f32_16x16x32_bf16 v[62:65], v[68:71], v[206:209], v[62:65]
	v_mfma_f32_16x16x32_bf16 v[58:61], v[86:89], v[206:209], v[58:61]
	v_mfma_f32_16x16x32_bf16 v[46:49], v[68:71], v[214:217], v[46:49]
	v_mfma_f32_16x16x32_bf16 v[42:45], v[86:89], v[214:217], v[42:45]
	v_mfma_f32_16x16x32_bf16 v[30:33], v[68:71], v[230:233], v[30:33]
	v_mfma_f32_16x16x32_bf16 v[26:29], v[86:89], v[230:233], v[26:29]
	v_mfma_f32_16x16x32_bf16 v[14:17], v[68:71], v[238:241], v[14:17]
	v_mfma_f32_16x16x32_bf16 v[10:13], v[86:89], v[238:241], v[10:13]
	v_mfma_f32_16x16x32_bf16 v[62:65], v[82:85], v[210:213], v[62:65]
	v_mfma_f32_16x16x32_bf16 v[58:61], v[146:149], v[210:213], v[58:61]
	v_mfma_f32_16x16x32_bf16 v[46:49], v[82:85], v[226:229], v[46:49]
	v_mfma_f32_16x16x32_bf16 v[42:45], v[146:149], v[226:229], v[42:45]
	v_mfma_f32_16x16x32_bf16 v[30:33], v[82:85], v[234:237], v[30:33]
	v_mfma_f32_16x16x32_bf16 v[26:29], v[146:149], v[234:237], v[26:29]
	v_mfma_f32_16x16x32_bf16 v[14:17], v[82:85], v[242:245], v[14:17]
	v_mfma_f32_16x16x32_bf16 v[10:13], v[146:149], v[242:245], v[10:13]
	v_mfma_f32_16x16x32_bf16 v[54:57], v[150:153], v[206:209], v[54:57]
	v_mfma_f32_16x16x32_bf16 v[50:53], v[158:161], v[206:209], v[50:53]
	v_mfma_f32_16x16x32_bf16 v[38:41], v[150:153], v[214:217], v[38:41]
	v_mfma_f32_16x16x32_bf16 v[34:37], v[158:161], v[214:217], v[34:37]
	v_mfma_f32_16x16x32_bf16 v[22:25], v[150:153], v[230:233], v[22:25]
	v_mfma_f32_16x16x32_bf16 v[18:21], v[158:161], v[230:233], v[18:21]
	v_mfma_f32_16x16x32_bf16 v[6:9], v[150:153], v[238:241], v[6:9]
	v_mfma_f32_16x16x32_bf16 v[2:5], v[158:161], v[238:241], v[2:5]
	v_mfma_f32_16x16x32_bf16 v[54:57], v[154:157], v[210:213], v[54:57]
	v_mfma_f32_16x16x32_bf16 v[50:53], v[202:205], v[210:213], v[50:53]
	v_mfma_f32_16x16x32_bf16 v[38:41], v[154:157], v[226:229], v[38:41]
	v_mfma_f32_16x16x32_bf16 v[34:37], v[202:205], v[226:229], v[34:37]
	v_mfma_f32_16x16x32_bf16 v[22:25], v[154:157], v[234:237], v[22:25]
	v_mfma_f32_16x16x32_bf16 v[18:21], v[202:205], v[234:237], v[18:21]
	v_mfma_f32_16x16x32_bf16 v[6:9], v[154:157], v[242:245], v[6:9]
	v_mfma_f32_16x16x32_bf16 v[2:5], v[202:205], v[242:245], v[2:5]
	s_setprio 0
	s_barrier
	s_add_i32 s57, 0, 0x18000
	v_add_u32_e32 v76, s57, v181
	s_add_i32 s60, 0, 0x1c000
	ds_read_b128 v[68:71], v76
	ds_read_b128 v[82:85], v76 offset:1024
	ds_read_b128 v[86:89], v76 offset:2048
	ds_read_b128 v[146:149], v76 offset:3072
	v_add_u32_e32 v76, s60, v181
	ds_read_b128 v[150:153], v76
	ds_read_b128 v[154:157], v76 offset:1024
	ds_read_b128 v[158:161], v76 offset:2048
	ds_read_b128 v[202:205], v76 offset:3072
	s_add_u32 s34, s34, 0x80000
	s_addc_u32 s35, s35, 0
	s_mov_b32 m0, s43
	v_lshl_add_u64 v[76:77], s[34:35], 0, v[166:167]
	ds_read_b128 v[206:209], v199 offset:32768
	ds_read_b128 v[210:213], v199 offset:33792
	ds_read_b128 v[214:217], v199 offset:34816
	ds_read_b128 v[226:229], v199 offset:35840
	ds_read_b128 v[230:233], v199 offset:36864
	ds_read_b128 v[234:237], v199 offset:37888
	ds_read_b128 v[238:241], v199 offset:38912
	ds_read_b128 v[242:245], v199 offset:39936
	global_load_lds_dwordx4 v[76:77], off
	v_lshl_add_u64 v[76:77], s[34:35], 0, v[164:165]
	s_mov_b32 m0, s44
	s_nop 0
	global_load_lds_dwordx4 v[76:77], off
	s_waitcnt vmcnt(8)
	s_waitcnt lgkmcnt(0)
	s_barrier
	s_setprio 1
	v_mfma_f32_16x16x32_bf16 v[142:145], v[68:71], v[206:209], v[142:145]
	v_mfma_f32_16x16x32_bf16 v[138:141], v[86:89], v[206:209], v[138:141]
	v_mfma_f32_16x16x32_bf16 v[126:129], v[68:71], v[214:217], v[126:129]
	v_mfma_f32_16x16x32_bf16 v[122:125], v[86:89], v[214:217], v[122:125]
	v_mfma_f32_16x16x32_bf16 v[110:113], v[68:71], v[230:233], v[110:113]
	v_mfma_f32_16x16x32_bf16 v[106:109], v[86:89], v[230:233], v[106:109]
	v_mfma_f32_16x16x32_bf16 v[94:97], v[68:71], v[238:241], v[94:97]
	v_mfma_f32_16x16x32_bf16 v[90:93], v[86:89], v[238:241], v[90:93]
	v_mfma_f32_16x16x32_bf16 v[142:145], v[82:85], v[210:213], v[142:145]
	v_mfma_f32_16x16x32_bf16 v[138:141], v[146:149], v[210:213], v[138:141]
	v_mfma_f32_16x16x32_bf16 v[126:129], v[82:85], v[226:229], v[126:129]
	v_mfma_f32_16x16x32_bf16 v[122:125], v[146:149], v[226:229], v[122:125]
	v_mfma_f32_16x16x32_bf16 v[110:113], v[82:85], v[234:237], v[110:113]
	v_mfma_f32_16x16x32_bf16 v[106:109], v[146:149], v[234:237], v[106:109]
	v_mfma_f32_16x16x32_bf16 v[94:97], v[82:85], v[242:245], v[94:97]
	v_mfma_f32_16x16x32_bf16 v[90:93], v[146:149], v[242:245], v[90:93]
	v_mfma_f32_16x16x32_bf16 v[134:137], v[150:153], v[206:209], v[134:137]
	v_mfma_f32_16x16x32_bf16 v[130:133], v[158:161], v[206:209], v[130:133]
	v_mfma_f32_16x16x32_bf16 v[118:121], v[150:153], v[214:217], v[118:121]
	v_mfma_f32_16x16x32_bf16 v[114:117], v[158:161], v[214:217], v[114:117]
	v_mfma_f32_16x16x32_bf16 v[102:105], v[150:153], v[230:233], v[102:105]
	v_mfma_f32_16x16x32_bf16 v[98:101], v[158:161], v[230:233], v[98:101]
	v_mfma_f32_16x16x32_bf16 v[76:79], v[150:153], v[238:241], v[78:81]
	v_mfma_f32_16x16x32_bf16 v[72:75], v[158:161], v[238:241], v[72:75]
	v_mfma_f32_16x16x32_bf16 v[134:137], v[154:157], v[210:213], v[134:137]
	v_mfma_f32_16x16x32_bf16 v[130:133], v[202:205], v[210:213], v[130:133]
	v_mfma_f32_16x16x32_bf16 v[118:121], v[154:157], v[226:229], v[118:121]
	v_mfma_f32_16x16x32_bf16 v[114:117], v[202:205], v[226:229], v[114:117]
	v_mfma_f32_16x16x32_bf16 v[102:105], v[154:157], v[234:237], v[102:105]
	v_mfma_f32_16x16x32_bf16 v[98:101], v[202:205], v[234:237], v[98:101]
	v_mfma_f32_16x16x32_bf16 v[78:81], v[154:157], v[242:245], v[76:79]
	v_mfma_f32_16x16x32_bf16 v[74:77], v[202:205], v[242:245], v[72:75]
	s_setprio 0
	s_barrier
	s_add_i32 s34, s57, s40
	v_lshl_add_u64 v[72:73], v[178:179], 0, s[96:97]
	s_mov_b32 m0, s34
	ds_read_b128 v[206:209], v199 offset:49152
	ds_read_b128 v[210:213], v199 offset:50176
	ds_read_b128 v[214:217], v199 offset:51200
	ds_read_b128 v[226:229], v199 offset:52224
	ds_read_b128 v[230:233], v199 offset:53248
	ds_read_b128 v[234:237], v199 offset:54272
	ds_read_b128 v[238:241], v199 offset:55296
	ds_read_b128 v[242:245], v199 offset:56320
	global_load_lds_dwordx4 v[72:73], off
	s_add_i32 m0, s34, 0x2000
	s_add_u32 s30, s30, 0x80080
	v_lshl_add_u64 v[72:73], v[250:251], 0, s[96:97]
	s_addc_u32 s31, s31, 0
	s_add_i32 s34, s60, s40
	global_load_lds_dwordx4 v[72:73], off
	v_lshl_add_u64 v[72:73], s[30:31], 0, v[0:1]
	s_mov_b32 m0, s34
	s_nop 0
	global_load_lds_dwordx4 v[72:73], off
	v_lshl_add_u64 v[72:73], s[30:31], 0, v[162:163]
	s_add_i32 m0, s34, 0x2000
	s_nop 0
	global_load_lds_dwordx4 v[72:73], off
	v_lshl_add_u64 v[72:73], v[252:253], 0, s[96:97]
	s_mov_b32 m0, s47
	s_nop 0
	global_load_lds_dwordx4 v[72:73], off
	v_lshl_add_u64 v[72:73], v[220:221], 0, s[96:97]
	s_mov_b32 m0, s50
	s_nop 0
	global_load_lds_dwordx4 v[72:73], off
	s_waitcnt vmcnt(8)
	s_waitcnt lgkmcnt(0)
	s_barrier
	s_setprio 1
	v_mfma_f32_16x16x32_bf16 v[62:65], v[68:71], v[206:209], v[62:65]
	v_mfma_f32_16x16x32_bf16 v[58:61], v[86:89], v[206:209], v[58:61]
	v_mfma_f32_16x16x32_bf16 v[46:49], v[68:71], v[214:217], v[46:49]
	v_mfma_f32_16x16x32_bf16 v[42:45], v[86:89], v[214:217], v[42:45]
	v_mfma_f32_16x16x32_bf16 v[30:33], v[68:71], v[230:233], v[30:33]
	v_mfma_f32_16x16x32_bf16 v[26:29], v[86:89], v[230:233], v[26:29]
	v_mfma_f32_16x16x32_bf16 v[14:17], v[68:71], v[238:241], v[14:17]
	v_mfma_f32_16x16x32_bf16 v[10:13], v[86:89], v[238:241], v[10:13]
	v_mfma_f32_16x16x32_bf16 v[62:65], v[82:85], v[210:213], v[62:65]
	v_mfma_f32_16x16x32_bf16 v[58:61], v[146:149], v[210:213], v[58:61]
	v_mfma_f32_16x16x32_bf16 v[46:49], v[82:85], v[226:229], v[46:49]
	v_mfma_f32_16x16x32_bf16 v[42:45], v[146:149], v[226:229], v[42:45]
	v_mfma_f32_16x16x32_bf16 v[30:33], v[82:85], v[234:237], v[30:33]
	v_mfma_f32_16x16x32_bf16 v[26:29], v[146:149], v[234:237], v[26:29]
	v_mfma_f32_16x16x32_bf16 v[14:17], v[82:85], v[242:245], v[14:17]
	v_mfma_f32_16x16x32_bf16 v[10:13], v[146:149], v[242:245], v[10:13]
	v_mfma_f32_16x16x32_bf16 v[54:57], v[150:153], v[206:209], v[54:57]
	v_mfma_f32_16x16x32_bf16 v[50:53], v[158:161], v[206:209], v[50:53]
	v_mfma_f32_16x16x32_bf16 v[38:41], v[150:153], v[214:217], v[38:41]
	v_mfma_f32_16x16x32_bf16 v[34:37], v[158:161], v[214:217], v[34:37]
	v_mfma_f32_16x16x32_bf16 v[22:25], v[150:153], v[230:233], v[22:25]
	v_mfma_f32_16x16x32_bf16 v[18:21], v[158:161], v[230:233], v[18:21]
	v_mfma_f32_16x16x32_bf16 v[6:9], v[150:153], v[238:241], v[6:9]
	v_mfma_f32_16x16x32_bf16 v[2:5], v[158:161], v[238:241], v[2:5]
	v_mfma_f32_16x16x32_bf16 v[54:57], v[154:157], v[210:213], v[54:57]
	v_mfma_f32_16x16x32_bf16 v[50:53], v[202:205], v[210:213], v[50:53]
	v_mfma_f32_16x16x32_bf16 v[38:41], v[154:157], v[226:229], v[38:41]
	v_mfma_f32_16x16x32_bf16 v[34:37], v[202:205], v[226:229], v[34:37]
	v_mfma_f32_16x16x32_bf16 v[22:25], v[154:157], v[234:237], v[22:25]
	v_mfma_f32_16x16x32_bf16 v[18:21], v[202:205], v[234:237], v[18:21]
	v_mfma_f32_16x16x32_bf16 v[6:9], v[154:157], v[242:245], v[6:9]
	v_mfma_f32_16x16x32_bf16 v[2:5], v[202:205], v[242:245], v[2:5]
	s_setprio 0
	s_barrier
	s_add_i32 s56, s56, 2
	s_add_u32 s1, s1, 0x100
	s_addc_u32 s55, s55, 0
	s_add_u32 s8, s8, 0x100
	s_addc_u32 s9, s9, 0
	s_cmp_gt_u32 s56, 29
	s_cbranch_scc1 .LBB0_273

.LBB0_616:
	s_ashr_i32 s27, s26, 31
	s_lshl_b64 s[28:29], s[26:27], 20
	s_add_u32 s28, s2, s28
	s_addc_u32 s29, s38, s29
	s_and_b64 s[30:31], s[6:7], exec
	s_cselect_b32 s21, s29, s35
	s_cselect_b32 s23, s28, s34
	s_ashr_i32 s25, s24, 31
	s_lshl_b64 s[30:31], s[24:25], 20
	s_add_u32 s30, s39, s30
	s_addc_u32 s31, s40, s31
	s_and_b64 s[36:37], s[6:7], exec
	s_cselect_b32 s25, s31, s9
	s_cselect_b32 s27, s30, s8
	s_add_u32 s61, s8, 0x100
	s_addc_u32 s62, s9, 0
	s_add_u32 s8, s34, 0x80080
	s_mov_b32 s98, 0
	s_addc_u32 s9, s35, 0
	s_mov_b32 s63, -2
.LBB0_617:
	s_add_u32 s34, s8, 0xfff80080
	s_addc_u32 s35, s9, -1
	s_add_i32 s64, 0, 0x10000
	s_cmp_eq_u32 s63, 28
	s_cselect_b32 s37, s21, s35
	s_cselect_b32 s36, s23, s34
	v_add_u32_e32 v0, s64, v212
	s_cselect_b32 s35, s25, s62
	s_cselect_b32 s34, s27, s61
	s_add_i32 s66, 0, 0x14000
	ds_read_b128 v[66:69], v0
	ds_read_b128 v[70:73], v0 offset:1024
	ds_read_b128 v[74:77], v0 offset:2048
	ds_read_b128 v[78:81], v0 offset:3072
	v_add_u32_e32 v0, s66, v212
	ds_read_b128 v[130:133], v0
	ds_read_b128 v[142:145], v0 offset:1024
	ds_read_b128 v[146:149], v0 offset:2048
	ds_read_b128 v[158:161], v0 offset:3072
	v_lshl_add_u64 v[220:221], s[8:9], 0, v[190:191]
	s_add_i32 m0, s42, 0xc000
	ds_read_b128 v[162:165], v215
	ds_read_b128 v[166:169], v215 offset:1024
	ds_read_b128 v[170:173], v215 offset:2048
	ds_read_b128 v[192:195], v215 offset:3072
	ds_read_b128 v[196:199], v215 offset:4096
	ds_read_b128 v[200:203], v215 offset:5120
	ds_read_b128 v[204:207], v215 offset:6144
	ds_read_b128 v[208:211], v215 offset:7168
	s_cmp_lg_u32 s98, 0
	s_cbranch_scc1 .Lzc_ph5_a
	v_mov_b64_e32 v[82:83], 0
	v_mov_b64_e32 v[84:85], 0
	v_mov_b64_e32 v[86:87], 0
	v_mov_b64_e32 v[88:89], 0
	v_mov_b64_e32 v[90:91], 0
	v_mov_b64_e32 v[92:93], 0
	v_mov_b64_e32 v[94:95], 0
	v_mov_b64_e32 v[96:97], 0
	v_mov_b64_e32 v[98:99], 0
	v_mov_b64_e32 v[100:101], 0
	v_mov_b64_e32 v[102:103], 0
	v_mov_b64_e32 v[104:105], 0
	v_mov_b64_e32 v[106:107], 0
	v_mov_b64_e32 v[108:109], 0
	v_mov_b64_e32 v[110:111], 0
	v_mov_b64_e32 v[112:113], 0
	v_mov_b64_e32 v[114:115], 0
	v_mov_b64_e32 v[116:117], 0
	v_mov_b64_e32 v[118:119], 0
	v_mov_b64_e32 v[120:121], 0
	v_mov_b64_e32 v[122:123], 0
	v_mov_b64_e32 v[124:125], 0
	v_mov_b64_e32 v[126:127], 0
	v_mov_b64_e32 v[128:129], 0
	v_mov_b64_e32 v[134:135], 0
	v_mov_b64_e32 v[136:137], 0
	v_mov_b64_e32 v[138:139], 0
	v_mov_b64_e32 v[140:141], 0
	v_mov_b64_e32 v[150:151], 0
	v_mov_b64_e32 v[152:153], 0
	v_mov_b64_e32 v[154:155], 0
	v_mov_b64_e32 v[156:157], 0
.Lzc_ph5_a:
	global_load_lds_dwordx4 v[220:221], off
	v_lshl_add_u64 v[220:221], s[8:9], 0, v[188:189]
	s_add_i32 m0, s42, 0xe000
	s_nop 0
	global_load_lds_dwordx4 v[220:221], off
	s_waitcnt vmcnt(8)
	s_waitcnt lgkmcnt(0)
	s_barrier
	s_setprio 1
	v_mfma_f32_16x16x32_bf16 v[154:157], v[66:69], v[162:165], v[154:157]
	v_mfma_f32_16x16x32_bf16 v[150:153], v[74:77], v[162:165], v[150:153]
	v_mfma_f32_16x16x32_bf16 v[138:141], v[66:69], v[170:173], v[138:141]
	v_mfma_f32_16x16x32_bf16 v[134:137], v[74:77], v[170:173], v[134:137]
	v_mfma_f32_16x16x32_bf16 v[110:113], v[66:69], v[196:199], v[110:113]
	v_mfma_f32_16x16x32_bf16 v[106:109], v[74:77], v[196:199], v[106:109]
	v_mfma_f32_16x16x32_bf16 v[94:97], v[66:69], v[204:207], v[94:97]
	v_mfma_f32_16x16x32_bf16 v[90:93], v[74:77], v[204:207], v[90:93]
	v_mfma_f32_16x16x32_bf16 v[154:157], v[70:73], v[166:169], v[154:157]
	v_mfma_f32_16x16x32_bf16 v[150:153], v[78:81], v[166:169], v[150:153]
	v_mfma_f32_16x16x32_bf16 v[138:141], v[70:73], v[192:195], v[138:141]
	v_mfma_f32_16x16x32_bf16 v[134:137], v[78:81], v[192:195], v[134:137]
	v_mfma_f32_16x16x32_bf16 v[110:113], v[70:73], v[200:203], v[110:113]
	v_mfma_f32_16x16x32_bf16 v[106:109], v[78:81], v[200:203], v[106:109]
	v_mfma_f32_16x16x32_bf16 v[94:97], v[70:73], v[208:211], v[94:97]
	v_mfma_f32_16x16x32_bf16 v[90:93], v[78:81], v[208:211], v[90:93]
	v_mfma_f32_16x16x32_bf16 v[126:129], v[130:133], v[162:165], v[126:129]
	v_mfma_f32_16x16x32_bf16 v[114:117], v[146:149], v[162:165], v[114:117]
	v_mfma_f32_16x16x32_bf16 v[122:125], v[130:133], v[170:173], v[122:125]
	v_mfma_f32_16x16x32_bf16 v[118:121], v[146:149], v[170:173], v[118:121]
	v_mfma_f32_16x16x32_bf16 v[102:105], v[130:133], v[196:199], v[102:105]
	v_mfma_f32_16x16x32_bf16 v[98:101], v[146:149], v[196:199], v[98:101]
	v_mfma_f32_16x16x32_bf16 v[86:89], v[130:133], v[204:207], v[86:89]
	v_mfma_f32_16x16x32_bf16 v[82:85], v[146:149], v[204:207], v[82:85]
	v_mfma_f32_16x16x32_bf16 v[126:129], v[142:145], v[166:169], v[126:129]
	v_mfma_f32_16x16x32_bf16 v[114:117], v[158:161], v[166:169], v[114:117]
	v_mfma_f32_16x16x32_bf16 v[122:125], v[142:145], v[192:195], v[122:125]
	v_mfma_f32_16x16x32_bf16 v[118:121], v[158:161], v[192:195], v[118:121]
	v_mfma_f32_16x16x32_bf16 v[102:105], v[142:145], v[200:203], v[102:105]
	v_mfma_f32_16x16x32_bf16 v[98:101], v[158:161], v[200:203], v[98:101]
	v_mfma_f32_16x16x32_bf16 v[86:89], v[142:145], v[208:211], v[86:89]
	v_mfma_f32_16x16x32_bf16 v[82:85], v[158:161], v[208:211], v[82:85]
	s_setprio 0
	s_barrier
	s_add_i32 s64, s64, s41
	v_lshl_add_u64 v[220:221], s[34:35], 0, v[182:183]
	s_mov_b32 m0, s64
	ds_read_b128 v[162:165], v215 offset:16384
	ds_read_b128 v[166:169], v215 offset:17408
	ds_read_b128 v[170:173], v215 offset:18432
	ds_read_b128 v[192:195], v215 offset:19456
	ds_read_b128 v[196:199], v215 offset:20480
	ds_read_b128 v[200:203], v215 offset:21504
	ds_read_b128 v[204:207], v215 offset:22528
	ds_read_b128 v[208:211], v215 offset:23552
	s_cmp_lg_u32 s98, 0
	s_cbranch_scc1 .Lzc_ph5_b
	v_mov_b64_e32 v[2:3], 0
	v_mov_b64_e32 v[4:5], 0
	v_mov_b64_e32 v[6:7], 0
	v_mov_b64_e32 v[8:9], 0
	v_mov_b64_e32 v[10:11], 0
	v_mov_b64_e32 v[12:13], 0
	v_mov_b64_e32 v[14:15], 0
	v_mov_b64_e32 v[16:17], 0
	v_mov_b64_e32 v[18:19], 0
	v_mov_b64_e32 v[20:21], 0
	v_mov_b64_e32 v[22:23], 0
	v_mov_b64_e32 v[24:25], 0
	v_mov_b64_e32 v[26:27], 0
	v_mov_b64_e32 v[28:29], 0
	v_mov_b64_e32 v[30:31], 0
	v_mov_b64_e32 v[32:33], 0
	v_mov_b64_e32 v[34:35], 0
	v_mov_b64_e32 v[36:37], 0
	v_mov_b64_e32 v[38:39], 0
	v_mov_b64_e32 v[40:41], 0
	v_mov_b64_e32 v[42:43], 0
	v_mov_b64_e32 v[44:45], 0
	v_mov_b64_e32 v[46:47], 0
	v_mov_b64_e32 v[48:49], 0
	v_mov_b64_e32 v[50:51], 0
	v_mov_b64_e32 v[52:53], 0
	v_mov_b64_e32 v[54:55], 0
	v_mov_b64_e32 v[56:57], 0
	v_mov_b64_e32 v[58:59], 0
	v_mov_b64_e32 v[60:61], 0
	v_mov_b64_e32 v[62:63], 0
	v_mov_b64_e32 v[64:65], 0
	s_mov_b32 s98, 1
.Lzc_ph5_b:
	global_load_lds_dwordx4 v[220:221], off
	s_add_i32 m0, s64, 0x2000
	s_add_u32 s64, s34, 0x80000
	v_lshl_add_u64 v[230:231], s[34:35], 0, v[178:179]
	s_addc_u32 s65, s35, 0
	s_add_i32 s66, s66, s41
	global_load_lds_dwordx4 v[230:231], off
	v_lshl_add_u64 v[232:233], s[64:65], 0, v[182:183]
	s_mov_b32 m0, s66
	v_lshl_add_u64 v[234:235], s[36:37], 0, v[180:181]
	global_load_lds_dwordx4 v[232:233], off
	v_lshl_add_u64 v[232:233], s[64:65], 0, v[178:179]
	s_add_i32 m0, s66, 0x2000
	s_nop 0
	global_load_lds_dwordx4 v[232:233], off
	v_lshl_add_u64 v[232:233], s[36:37], 0, v[184:185]
	s_mov_b32 m0, s42
	s_nop 0
	global_load_lds_dwordx4 v[232:233], off
	s_mov_b32 m0, s43
	s_nop 0
	global_load_lds_dwordx4 v[234:235], off
	s_waitcnt vmcnt(8)
	s_waitcnt lgkmcnt(0)
	s_barrier
	s_setprio 1
	v_mfma_f32_16x16x32_bf16 v[62:65], v[66:69], v[162:165], v[62:65]
	v_mfma_f32_16x16x32_bf16 v[58:61], v[74:77], v[162:165], v[58:61]
	v_mfma_f32_16x16x32_bf16 v[46:49], v[66:69], v[170:173], v[46:49]
	v_mfma_f32_16x16x32_bf16 v[42:45], v[74:77], v[170:173], v[42:45]
	v_mfma_f32_16x16x32_bf16 v[30:33], v[66:69], v[196:199], v[30:33]
	v_mfma_f32_16x16x32_bf16 v[26:29], v[74:77], v[196:199], v[26:29]
	v_mfma_f32_16x16x32_bf16 v[14:17], v[66:69], v[204:207], v[14:17]
	v_mfma_f32_16x16x32_bf16 v[10:13], v[74:77], v[204:207], v[10:13]
	v_mfma_f32_16x16x32_bf16 v[62:65], v[70:73], v[166:169], v[62:65]
	v_mfma_f32_16x16x32_bf16 v[58:61], v[78:81], v[166:169], v[58:61]
	v_mfma_f32_16x16x32_bf16 v[46:49], v[70:73], v[192:195], v[46:49]
	v_mfma_f32_16x16x32_bf16 v[42:45], v[78:81], v[192:195], v[42:45]
	v_mfma_f32_16x16x32_bf16 v[30:33], v[70:73], v[200:203], v[30:33]
	v_mfma_f32_16x16x32_bf16 v[26:29], v[78:81], v[200:203], v[26:29]
	v_mfma_f32_16x16x32_bf16 v[14:17], v[70:73], v[208:211], v[14:17]
	v_mfma_f32_16x16x32_bf16 v[10:13], v[78:81], v[208:211], v[10:13]
	v_mfma_f32_16x16x32_bf16 v[54:57], v[130:133], v[162:165], v[54:57]
	v_mfma_f32_16x16x32_bf16 v[50:53], v[146:149], v[162:165], v[50:53]
	v_mfma_f32_16x16x32_bf16 v[38:41], v[130:133], v[170:173], v[38:41]
	v_mfma_f32_16x16x32_bf16 v[34:37], v[146:149], v[170:173], v[34:37]
	v_mfma_f32_16x16x32_bf16 v[22:25], v[130:133], v[196:199], v[22:25]
	v_mfma_f32_16x16x32_bf16 v[18:21], v[146:149], v[196:199], v[18:21]
	v_mfma_f32_16x16x32_bf16 v[6:9], v[130:133], v[204:207], v[6:9]
	v_mfma_f32_16x16x32_bf16 v[2:5], v[146:149], v[204:207], v[2:5]
	v_mfma_f32_16x16x32_bf16 v[54:57], v[142:145], v[166:169], v[54:57]
	v_mfma_f32_16x16x32_bf16 v[50:53], v[158:161], v[166:169], v[50:53]
	v_mfma_f32_16x16x32_bf16 v[38:41], v[142:145], v[192:195], v[38:41]
	v_mfma_f32_16x16x32_bf16 v[34:37], v[158:161], v[192:195], v[34:37]
	v_mfma_f32_16x16x32_bf16 v[22:25], v[142:145], v[200:203], v[22:25]
	v_mfma_f32_16x16x32_bf16 v[18:21], v[158:161], v[200:203], v[18:21]
	v_mfma_f32_16x16x32_bf16 v[6:9], v[142:145], v[208:211], v[6:9]
	v_mfma_f32_16x16x32_bf16 v[2:5], v[158:161], v[208:211], v[2:5]
	s_setprio 0
	s_barrier
	s_add_i32 s64, 0, 0x18000
	v_add_u32_e32 v0, s64, v212
	s_add_i32 s65, 0, 0x1c000
	ds_read_b128 v[66:69], v0
	ds_read_b128 v[70:73], v0 offset:1024
	ds_read_b128 v[74:77], v0 offset:2048
	ds_read_b128 v[78:81], v0 offset:3072
	v_add_u32_e32 v0, s65, v212
	ds_read_b128 v[130:133], v0
	ds_read_b128 v[142:145], v0 offset:1024
	ds_read_b128 v[146:149], v0 offset:2048
	ds_read_b128 v[158:161], v0 offset:3072
	s_add_u32 s36, s36, 0x80000
	s_addc_u32 s37, s37, 0
	s_mov_b32 m0, s44
	v_lshl_add_u64 v[236:237], s[36:37], 0, v[184:185]
	ds_read_b128 v[162:165], v215 offset:32768
	ds_read_b128 v[166:169], v215 offset:33792
	ds_read_b128 v[170:173], v215 offset:34816
	ds_read_b128 v[192:195], v215 offset:35840
	ds_read_b128 v[196:199], v215 offset:36864
	ds_read_b128 v[200:203], v215 offset:37888
	ds_read_b128 v[204:207], v215 offset:38912
	ds_read_b128 v[208:211], v215 offset:39936
	global_load_lds_dwordx4 v[236:237], off
	v_lshl_add_u64 v[236:237], s[36:37], 0, v[180:181]
	s_mov_b32 m0, s45
	s_nop 0
	global_load_lds_dwordx4 v[236:237], off
	s_waitcnt vmcnt(8)
	s_waitcnt lgkmcnt(0)
	s_barrier
	s_setprio 1
	v_mfma_f32_16x16x32_bf16 v[154:157], v[66:69], v[162:165], v[154:157]
	v_mfma_f32_16x16x32_bf16 v[150:153], v[74:77], v[162:165], v[150:153]
	v_mfma_f32_16x16x32_bf16 v[138:141], v[66:69], v[170:173], v[138:141]
	v_mfma_f32_16x16x32_bf16 v[134:137], v[74:77], v[170:173], v[134:137]
	v_mfma_f32_16x16x32_bf16 v[110:113], v[66:69], v[196:199], v[110:113]
	v_mfma_f32_16x16x32_bf16 v[106:109], v[74:77], v[196:199], v[106:109]
	v_mfma_f32_16x16x32_bf16 v[94:97], v[66:69], v[204:207], v[94:97]
	v_mfma_f32_16x16x32_bf16 v[90:93], v[74:77], v[204:207], v[90:93]
	v_mfma_f32_16x16x32_bf16 v[154:157], v[70:73], v[166:169], v[154:157]
	v_mfma_f32_16x16x32_bf16 v[150:153], v[78:81], v[166:169], v[150:153]
	v_mfma_f32_16x16x32_bf16 v[138:141], v[70:73], v[192:195], v[138:141]
	v_mfma_f32_16x16x32_bf16 v[134:137], v[78:81], v[192:195], v[134:137]
	v_mfma_f32_16x16x32_bf16 v[110:113], v[70:73], v[200:203], v[110:113]
	v_mfma_f32_16x16x32_bf16 v[106:109], v[78:81], v[200:203], v[106:109]
	v_mfma_f32_16x16x32_bf16 v[94:97], v[70:73], v[208:211], v[94:97]
	v_mfma_f32_16x16x32_bf16 v[90:93], v[78:81], v[208:211], v[90:93]
	v_mfma_f32_16x16x32_bf16 v[126:129], v[130:133], v[162:165], v[126:129]
	v_mfma_f32_16x16x32_bf16 v[114:117], v[146:149], v[162:165], v[114:117]
	v_mfma_f32_16x16x32_bf16 v[122:125], v[130:133], v[170:173], v[122:125]
	v_mfma_f32_16x16x32_bf16 v[118:121], v[146:149], v[170:173], v[118:121]
	v_mfma_f32_16x16x32_bf16 v[102:105], v[130:133], v[196:199], v[102:105]
	v_mfma_f32_16x16x32_bf16 v[98:101], v[146:149], v[196:199], v[98:101]
	v_mfma_f32_16x16x32_bf16 v[86:89], v[130:133], v[204:207], v[86:89]
	v_mfma_f32_16x16x32_bf16 v[82:85], v[146:149], v[204:207], v[82:85]
	v_mfma_f32_16x16x32_bf16 v[126:129], v[142:145], v[166:169], v[126:129]
	v_mfma_f32_16x16x32_bf16 v[114:117], v[158:161], v[166:169], v[114:117]
	v_mfma_f32_16x16x32_bf16 v[122:125], v[142:145], v[192:195], v[122:125]
	v_mfma_f32_16x16x32_bf16 v[118:121], v[158:161], v[192:195], v[118:121]
	v_mfma_f32_16x16x32_bf16 v[102:105], v[142:145], v[200:203], v[102:105]
	v_mfma_f32_16x16x32_bf16 v[98:101], v[158:161], v[200:203], v[98:101]
	v_mfma_f32_16x16x32_bf16 v[86:89], v[142:145], v[208:211], v[86:89]
	v_mfma_f32_16x16x32_bf16 v[82:85], v[158:161], v[208:211], v[82:85]
	s_setprio 0
	s_barrier
	s_add_i32 s36, s64, s41
	v_lshl_add_u64 v[220:221], v[220:221], 0, s[96:97]
	s_mov_b32 m0, s36
	ds_read_b128 v[162:165], v215 offset:49152
	ds_read_b128 v[166:169], v215 offset:50176
	ds_read_b128 v[170:173], v215 offset:51200
	ds_read_b128 v[192:195], v215 offset:52224
	ds_read_b128 v[196:199], v215 offset:53248
	ds_read_b128 v[200:203], v215 offset:54272
	ds_read_b128 v[204:207], v215 offset:55296
	ds_read_b128 v[208:211], v215 offset:56320
	global_load_lds_dwordx4 v[220:221], off
	s_add_i32 m0, s36, 0x2000
	s_add_u32 s34, s34, 0x80080
	v_lshl_add_u64 v[220:221], v[230:231], 0, s[96:97]
	s_addc_u32 s35, s35, 0
	s_add_i32 s36, s65, s41
	global_load_lds_dwordx4 v[220:221], off
	v_lshl_add_u64 v[220:221], s[34:35], 0, v[182:183]
	s_mov_b32 m0, s36
	s_nop 0
	global_load_lds_dwordx4 v[220:221], off
	v_lshl_add_u64 v[220:221], s[34:35], 0, v[178:179]
	s_add_i32 m0, s36, 0x2000
	s_nop 0
	global_load_lds_dwordx4 v[220:221], off
	v_lshl_add_u64 v[220:221], v[232:233], 0, s[96:97]
	s_mov_b32 m0, s56
	s_nop 0
	global_load_lds_dwordx4 v[220:221], off
	v_lshl_add_u64 v[220:221], v[234:235], 0, s[96:97]
	s_mov_b32 m0, s57
	s_nop 0
	global_load_lds_dwordx4 v[220:221], off
	s_waitcnt vmcnt(8)
	s_waitcnt lgkmcnt(0)
	s_barrier
	s_setprio 1
	v_mfma_f32_16x16x32_bf16 v[62:65], v[66:69], v[162:165], v[62:65]
	v_mfma_f32_16x16x32_bf16 v[58:61], v[74:77], v[162:165], v[58:61]
	v_mfma_f32_16x16x32_bf16 v[46:49], v[66:69], v[170:173], v[46:49]
	v_mfma_f32_16x16x32_bf16 v[42:45], v[74:77], v[170:173], v[42:45]
	v_mfma_f32_16x16x32_bf16 v[30:33], v[66:69], v[196:199], v[30:33]
	v_mfma_f32_16x16x32_bf16 v[26:29], v[74:77], v[196:199], v[26:29]
	v_mfma_f32_16x16x32_bf16 v[14:17], v[66:69], v[204:207], v[14:17]
	v_mfma_f32_16x16x32_bf16 v[10:13], v[74:77], v[204:207], v[10:13]
	v_mfma_f32_16x16x32_bf16 v[62:65], v[70:73], v[166:169], v[62:65]
	v_mfma_f32_16x16x32_bf16 v[58:61], v[78:81], v[166:169], v[58:61]
	v_mfma_f32_16x16x32_bf16 v[46:49], v[70:73], v[192:195], v[46:49]
	v_mfma_f32_16x16x32_bf16 v[42:45], v[78:81], v[192:195], v[42:45]
	v_mfma_f32_16x16x32_bf16 v[30:33], v[70:73], v[200:203], v[30:33]
	v_mfma_f32_16x16x32_bf16 v[26:29], v[78:81], v[200:203], v[26:29]
	v_mfma_f32_16x16x32_bf16 v[14:17], v[70:73], v[208:211], v[14:17]
	v_mfma_f32_16x16x32_bf16 v[10:13], v[78:81], v[208:211], v[10:13]
	v_mfma_f32_16x16x32_bf16 v[54:57], v[130:133], v[162:165], v[54:57]
	v_mfma_f32_16x16x32_bf16 v[50:53], v[146:149], v[162:165], v[50:53]
	v_mfma_f32_16x16x32_bf16 v[38:41], v[130:133], v[170:173], v[38:41]
	v_mfma_f32_16x16x32_bf16 v[34:37], v[146:149], v[170:173], v[34:37]
	v_mfma_f32_16x16x32_bf16 v[22:25], v[130:133], v[196:199], v[22:25]
	v_mfma_f32_16x16x32_bf16 v[18:21], v[146:149], v[196:199], v[18:21]
	v_mfma_f32_16x16x32_bf16 v[6:9], v[130:133], v[204:207], v[6:9]
	v_mfma_f32_16x16x32_bf16 v[2:5], v[146:149], v[204:207], v[2:5]
	v_mfma_f32_16x16x32_bf16 v[54:57], v[142:145], v[166:169], v[54:57]
	v_mfma_f32_16x16x32_bf16 v[50:53], v[158:161], v[166:169], v[50:53]
	v_mfma_f32_16x16x32_bf16 v[38:41], v[142:145], v[192:195], v[38:41]
	v_mfma_f32_16x16x32_bf16 v[34:37], v[158:161], v[192:195], v[34:37]
	v_mfma_f32_16x16x32_bf16 v[22:25], v[142:145], v[200:203], v[22:25]
	v_mfma_f32_16x16x32_bf16 v[18:21], v[158:161], v[200:203], v[18:21]
	v_mfma_f32_16x16x32_bf16 v[6:9], v[142:145], v[208:211], v[6:9]
	v_mfma_f32_16x16x32_bf16 v[2:5], v[158:161], v[208:211], v[2:5]
	s_setprio 0
	s_barrier
	s_add_i32 s63, s63, 2
	s_add_u32 s61, s61, 0x100
	s_addc_u32 s62, s62, 0
	s_add_u32 s8, s8, 0x100
	s_addc_u32 s9, s9, 0
	s_cmp_gt_u32 s63, 29
	s_cbranch_scc0 .LBB0_617
	s_and_b64 vcc, exec, s[14:15]
	s_cbranch_vccz .LBB0_620
	s_barrier

.LBB0_742:
	s_ashr_i32 s31, s30, 31
	s_lshl_b64 s[12:13], s[30:31], 20
	s_add_u32 s34, s2, s12
	s_addc_u32 s35, s52, s13
	s_and_b64 s[12:13], s[10:11], exec
	s_cselect_b32 s31, s35, s39
	s_cselect_b32 s88, s34, s38
	s_ashr_i32 s29, s28, 31
	s_lshl_b64 s[12:13], s[28:29], 20
	s_add_u32 s36, s53, s12
	s_addc_u32 s37, s54, s13
	s_and_b64 s[12:13], s[10:11], exec
	s_cselect_b32 s29, s37, s45
	s_cselect_b32 s90, s36, s44
	s_ashr_i32 s41, s40, 31
	s_lshl_b64 s[12:13], s[40:41], 13
	s_ashr_i32 s41, s40, 5
	s_lshl_b32 s46, s42, 8
	s_lshl_b32 s42, s42, 7
	s_mul_hi_i32 s50, s41, 0xb000
	s_mul_i32 s41, s41, 0xb000
	s_ashr_i32 s47, s46, 31
	s_ashr_i32 s43, s42, 31
	s_add_u32 s41, s69, s41
	v_lshl_add_u64 v[66:67], v[170:171], 0, s[12:13]
	s_addc_u32 s50, s73, s50
	s_lshl_b64 s[12:13], s[46:47], 2
	s_add_u32 s41, s41, s12
	s_addc_u32 s46, s50, s13
	s_lshl_b64 s[12:13], s[42:43], 2
	s_add_u32 s43, s81, s12
	s_addc_u32 s47, s84, s13
	v_mov_b32_e32 v2, s46
	v_mov_b32_e32 v3, s47
	v_lshl_add_u64 v[70:71], v[172:173], 0, s[12:13]
	s_add_u32 s12, s41, 0x200
	v_cndmask_b32_e64 v69, v2, v3, s[14:15]
	v_mov_b32_e32 v2, s41
	v_mov_b32_e32 v3, s43
	s_addc_u32 s13, s46, 0
	v_cndmask_b32_e64 v68, v2, v3, s[14:15]
	s_add_u32 s41, s44, 0x100
	s_mov_b32 s98, 0
	s_addc_u32 s43, s45, 0
	s_mov_b32 s91, -2
	s_branch .LBB0_745

.LBB0_744:
	s_add_u32 s44, s38, 0x100
	s_addc_u32 s45, s39, 0
	s_and_b64 s[46:47], s[46:47], exec
	s_cselect_b32 s51, s31, s45
	s_cselect_b32 s50, s88, s44
	s_cselect_b32 s47, s29, s43
	s_cselect_b32 s46, s90, s41
	s_add_i32 s93, 0, 0x10000
	s_add_i32 s94, 0, 0x14000
	v_add_u32_e32 v84, s93, v226
	v_add_u32_e32 v88, s94, v226
	ds_read_b128 v[72:75], v84
	ds_read_b128 v[76:79], v84 offset:1024
	ds_read_b128 v[80:83], v84 offset:2048
	ds_read_b128 v[84:87], v84 offset:3072
	ds_read_b128 v[154:157], v88
	ds_read_b128 v[158:161], v88 offset:1024
	ds_read_b128 v[182:185], v88 offset:2048
	ds_read_b128 v[186:189], v88 offset:3072
	v_lshl_add_u64 v[88:89], s[38:39], 0, v[180:181]
	s_add_i32 m0, s56, 0xc000
	ds_read_b128 v[190:193], v230
	ds_read_b128 v[194:197], v230 offset:1024
	ds_read_b128 v[198:201], v230 offset:2048
	ds_read_b128 v[202:205], v230 offset:3072
	ds_read_b128 v[206:209], v230 offset:4096
	ds_read_b128 v[210:213], v230 offset:5120
	ds_read_b128 v[214:217], v230 offset:6144
	ds_read_b128 v[236:239], v230 offset:7168
	s_cmp_lg_u32 s98, 0
	s_cbranch_scc1 .Lzc_ph7_a
	v_mov_b64_e32 v[90:91], 0
	v_mov_b64_e32 v[92:93], 0
	v_mov_b64_e32 v[94:95], 0
	v_mov_b64_e32 v[96:97], 0
	v_mov_b64_e32 v[98:99], 0
	v_mov_b64_e32 v[100:101], 0
	v_mov_b64_e32 v[102:103], 0
	v_mov_b64_e32 v[104:105], 0
	v_mov_b64_e32 v[106:107], 0
	v_mov_b64_e32 v[108:109], 0
	v_mov_b64_e32 v[110:111], 0
	v_mov_b64_e32 v[112:113], 0
	v_mov_b64_e32 v[114:115], 0
	v_mov_b64_e32 v[116:117], 0
	v_mov_b64_e32 v[118:119], 0
	v_mov_b64_e32 v[120:121], 0
	v_mov_b64_e32 v[122:123], 0
	v_mov_b64_e32 v[124:125], 0
	v_mov_b64_e32 v[126:127], 0
	v_mov_b64_e32 v[128:129], 0
	v_mov_b64_e32 v[130:131], 0
	v_mov_b64_e32 v[132:133], 0
	v_mov_b64_e32 v[134:135], 0
	v_mov_b64_e32 v[136:137], 0
	v_mov_b64_e32 v[138:139], 0
	v_mov_b64_e32 v[140:141], 0
	v_mov_b64_e32 v[142:143], 0
	v_mov_b64_e32 v[144:145], 0
	v_mov_b64_e32 v[146:147], 0
	v_mov_b64_e32 v[148:149], 0
	v_mov_b64_e32 v[150:151], 0
	v_mov_b64_e32 v[152:153], 0
.Lzc_ph7_a:
	global_load_lds_dwordx4 v[88:89], off
	v_lshl_add_u64 v[88:89], s[38:39], 0, v[178:179]
	s_add_i32 m0, s56, 0xe000
	s_nop 0
	global_load_lds_dwordx4 v[88:89], off
	s_waitcnt vmcnt(8)
	s_waitcnt lgkmcnt(0)
	s_barrier
	s_setprio 1
	v_mfma_f32_16x16x32_bf16 v[150:153], v[72:75], v[190:193], v[150:153]
	v_mfma_f32_16x16x32_bf16 v[146:149], v[80:83], v[190:193], v[146:149]
	v_mfma_f32_16x16x32_bf16 v[118:121], v[72:75], v[198:201], v[118:121]
	v_mfma_f32_16x16x32_bf16 v[114:117], v[80:83], v[198:201], v[114:117]
	v_mfma_f32_16x16x32_bf16 v[142:145], v[72:75], v[206:209], v[142:145]
	v_mfma_f32_16x16x32_bf16 v[134:137], v[80:83], v[206:209], v[134:137]
	v_mfma_f32_16x16x32_bf16 v[126:129], v[72:75], v[214:217], v[126:129]
	v_mfma_f32_16x16x32_bf16 v[122:125], v[80:83], v[214:217], v[122:125]
	v_mfma_f32_16x16x32_bf16 v[150:153], v[76:79], v[194:197], v[150:153]
	v_mfma_f32_16x16x32_bf16 v[146:149], v[84:87], v[194:197], v[146:149]
	v_mfma_f32_16x16x32_bf16 v[118:121], v[76:79], v[202:205], v[118:121]
	v_mfma_f32_16x16x32_bf16 v[114:117], v[84:87], v[202:205], v[114:117]
	v_mfma_f32_16x16x32_bf16 v[142:145], v[76:79], v[210:213], v[142:145]
	v_mfma_f32_16x16x32_bf16 v[134:137], v[84:87], v[210:213], v[134:137]
	v_mfma_f32_16x16x32_bf16 v[126:129], v[76:79], v[236:239], v[126:129]
	v_mfma_f32_16x16x32_bf16 v[122:125], v[84:87], v[236:239], v[122:125]
	v_mfma_f32_16x16x32_bf16 v[138:141], v[154:157], v[190:193], v[138:141]
	v_mfma_f32_16x16x32_bf16 v[130:133], v[182:185], v[190:193], v[130:133]
	v_mfma_f32_16x16x32_bf16 v[110:113], v[154:157], v[198:201], v[110:113]
	v_mfma_f32_16x16x32_bf16 v[106:109], v[182:185], v[198:201], v[106:109]
	v_mfma_f32_16x16x32_bf16 v[102:105], v[154:157], v[206:209], v[102:105]
	v_mfma_f32_16x16x32_bf16 v[98:101], v[182:185], v[206:209], v[98:101]
	v_mfma_f32_16x16x32_bf16 v[94:97], v[154:157], v[214:217], v[94:97]
	v_mfma_f32_16x16x32_bf16 v[88:91], v[182:185], v[214:217], v[90:93]
	v_mfma_f32_16x16x32_bf16 v[138:141], v[158:161], v[194:197], v[138:141]
	v_mfma_f32_16x16x32_bf16 v[130:133], v[186:189], v[194:197], v[130:133]
	v_mfma_f32_16x16x32_bf16 v[110:113], v[158:161], v[202:205], v[110:113]
	v_mfma_f32_16x16x32_bf16 v[106:109], v[186:189], v[202:205], v[106:109]
	v_mfma_f32_16x16x32_bf16 v[102:105], v[158:161], v[210:213], v[102:105]
	v_mfma_f32_16x16x32_bf16 v[98:101], v[186:189], v[210:213], v[98:101]
	v_mfma_f32_16x16x32_bf16 v[94:97], v[158:161], v[236:239], v[94:97]
	v_mfma_f32_16x16x32_bf16 v[88:91], v[186:189], v[236:239], v[88:91]
	s_setprio 0
	s_barrier
	s_add_i32 s38, s93, s55
	v_lshl_add_u64 v[220:221], s[46:47], 0, v[166:167]
	s_mov_b32 m0, s38
	ds_read_b128 v[190:193], v230 offset:16384
	ds_read_b128 v[194:197], v230 offset:17408
	ds_read_b128 v[198:201], v230 offset:18432
	ds_read_b128 v[202:205], v230 offset:19456
	ds_read_b128 v[206:209], v230 offset:20480
	ds_read_b128 v[210:213], v230 offset:21504
	ds_read_b128 v[214:217], v230 offset:22528
	ds_read_b128 v[236:239], v230 offset:23552
	s_cmp_lg_u32 s98, 0
	s_cbranch_scc1 .Lzc_ph7_b
	v_mov_b64_e32 v[2:3], 0
	v_mov_b64_e32 v[4:5], 0
	v_mov_b64_e32 v[6:7], 0
	v_mov_b64_e32 v[8:9], 0
	v_mov_b64_e32 v[10:11], 0
	v_mov_b64_e32 v[12:13], 0
	v_mov_b64_e32 v[14:15], 0
	v_mov_b64_e32 v[16:17], 0
	v_mov_b64_e32 v[18:19], 0
	v_mov_b64_e32 v[20:21], 0
	v_mov_b64_e32 v[22:23], 0
	v_mov_b64_e32 v[24:25], 0
	v_mov_b64_e32 v[26:27], 0
	v_mov_b64_e32 v[28:29], 0
	v_mov_b64_e32 v[30:31], 0
	v_mov_b64_e32 v[32:33], 0
	v_mov_b64_e32 v[34:35], 0
	v_mov_b64_e32 v[36:37], 0
	v_mov_b64_e32 v[38:39], 0
	v_mov_b64_e32 v[40:41], 0
	v_mov_b64_e32 v[42:43], 0
	v_mov_b64_e32 v[44:45], 0
	v_mov_b64_e32 v[46:47], 0
	v_mov_b64_e32 v[48:49], 0
	v_mov_b64_e32 v[50:51], 0
	v_mov_b64_e32 v[52:53], 0
	v_mov_b64_e32 v[54:55], 0
	v_mov_b64_e32 v[56:57], 0
	v_mov_b64_e32 v[58:59], 0
	v_mov_b64_e32 v[60:61], 0
	v_mov_b64_e32 v[62:63], 0
	v_mov_b64_e32 v[64:65], 0
	s_mov_b32 s98, 1
.Lzc_ph7_b:
	global_load_lds_dwordx4 v[220:221], off
	s_add_i32 m0, s38, 0x2000
	s_add_u32 s38, s46, 0x80000
	v_lshl_add_u64 v[240:241], s[46:47], 0, v[162:163]
	s_addc_u32 s39, s47, 0
	s_add_i32 s93, s94, s55
	global_load_lds_dwordx4 v[240:241], off
	v_lshl_add_u64 v[92:93], s[38:39], 0, v[166:167]
	s_mov_b32 m0, s93
	v_lshl_add_u64 v[242:243], s[50:51], 0, v[168:169]
	global_load_lds_dwordx4 v[92:93], off
	v_lshl_add_u64 v[92:93], s[38:39], 0, v[162:163]
	s_add_i32 m0, s93, 0x2000
	v_lshl_add_u64 v[244:245], s[50:51], 0, v[164:165]
	global_load_lds_dwordx4 v[92:93], off
	s_mov_b32 m0, s56
	s_nop 0
	global_load_lds_dwordx4 v[242:243], off
	s_mov_b32 m0, s57
	s_nop 0
	global_load_lds_dwordx4 v[244:245], off
	s_waitcnt vmcnt(8)
	s_waitcnt lgkmcnt(0)
	s_barrier
	s_setprio 1
	v_mfma_f32_16x16x32_bf16 v[62:65], v[72:75], v[190:193], v[62:65]
	v_mfma_f32_16x16x32_bf16 v[58:61], v[80:83], v[190:193], v[58:61]
	v_mfma_f32_16x16x32_bf16 v[54:57], v[72:75], v[198:201], v[54:57]
	v_mfma_f32_16x16x32_bf16 v[46:49], v[80:83], v[198:201], v[46:49]
	v_mfma_f32_16x16x32_bf16 v[38:41], v[72:75], v[206:209], v[38:41]
	v_mfma_f32_16x16x32_bf16 v[30:33], v[80:83], v[206:209], v[30:33]
	v_mfma_f32_16x16x32_bf16 v[22:25], v[72:75], v[214:217], v[22:25]
	v_mfma_f32_16x16x32_bf16 v[14:17], v[80:83], v[214:217], v[14:17]
	v_mfma_f32_16x16x32_bf16 v[62:65], v[76:79], v[194:197], v[62:65]
	v_mfma_f32_16x16x32_bf16 v[58:61], v[84:87], v[194:197], v[58:61]
	v_mfma_f32_16x16x32_bf16 v[54:57], v[76:79], v[202:205], v[54:57]
	v_mfma_f32_16x16x32_bf16 v[46:49], v[84:87], v[202:205], v[46:49]
	v_mfma_f32_16x16x32_bf16 v[38:41], v[76:79], v[210:213], v[38:41]
	v_mfma_f32_16x16x32_bf16 v[30:33], v[84:87], v[210:213], v[30:33]
	v_mfma_f32_16x16x32_bf16 v[22:25], v[76:79], v[236:239], v[22:25]
	v_mfma_f32_16x16x32_bf16 v[14:17], v[84:87], v[236:239], v[14:17]
	v_mfma_f32_16x16x32_bf16 v[50:53], v[154:157], v[190:193], v[50:53]
	v_mfma_f32_16x16x32_bf16 v[42:45], v[182:185], v[190:193], v[42:45]
	v_mfma_f32_16x16x32_bf16 v[34:37], v[154:157], v[198:201], v[34:37]
	v_mfma_f32_16x16x32_bf16 v[26:29], v[182:185], v[198:201], v[26:29]
	v_mfma_f32_16x16x32_bf16 v[18:21], v[154:157], v[206:209], v[18:21]
	v_mfma_f32_16x16x32_bf16 v[10:13], v[182:185], v[206:209], v[10:13]
	v_mfma_f32_16x16x32_bf16 v[6:9], v[154:157], v[214:217], v[6:9]
	v_mfma_f32_16x16x32_bf16 v[2:5], v[182:185], v[214:217], v[2:5]
	v_mfma_f32_16x16x32_bf16 v[50:53], v[158:161], v[194:197], v[50:53]
	v_mfma_f32_16x16x32_bf16 v[42:45], v[186:189], v[194:197], v[42:45]
	v_mfma_f32_16x16x32_bf16 v[34:37], v[158:161], v[202:205], v[34:37]
	v_mfma_f32_16x16x32_bf16 v[26:29], v[186:189], v[202:205], v[26:29]
	v_mfma_f32_16x16x32_bf16 v[18:21], v[158:161], v[210:213], v[18:21]
	v_mfma_f32_16x16x32_bf16 v[10:13], v[186:189], v[210:213], v[10:13]
	v_mfma_f32_16x16x32_bf16 v[6:9], v[158:161], v[236:239], v[6:9]
	v_mfma_f32_16x16x32_bf16 v[2:5], v[186:189], v[236:239], v[2:5]
	s_setprio 0
	s_barrier
	s_add_i32 s93, 0, 0x18000
	s_add_i32 s94, 0, 0x1c000
	v_add_u32_e32 v84, s93, v226
	v_add_u32_e32 v92, s94, v226
	ds_read_b128 v[72:75], v84
	ds_read_b128 v[76:79], v84 offset:1024
	ds_read_b128 v[80:83], v84 offset:2048
	ds_read_b128 v[84:87], v84 offset:3072
	ds_read_b128 v[154:157], v92
	ds_read_b128 v[158:161], v92 offset:1024
	ds_read_b128 v[182:185], v92 offset:2048
	ds_read_b128 v[186:189], v92 offset:3072
	s_add_u32 s38, s50, 0x80000
	s_addc_u32 s39, s51, 0
	s_mov_b32 m0, s60
	v_lshl_add_u64 v[92:93], s[38:39], 0, v[168:169]
	ds_read_b128 v[190:193], v230 offset:32768
	ds_read_b128 v[194:197], v230 offset:33792
	ds_read_b128 v[198:201], v230 offset:34816
	ds_read_b128 v[202:205], v230 offset:35840
	ds_read_b128 v[206:209], v230 offset:36864
	ds_read_b128 v[210:213], v230 offset:37888
	ds_read_b128 v[214:217], v230 offset:38912
	ds_read_b128 v[236:239], v230 offset:39936
	global_load_lds_dwordx4 v[92:93], off
	v_lshl_add_u64 v[92:93], s[38:39], 0, v[164:165]
	s_mov_b32 m0, s61
	s_nop 0
	global_load_lds_dwordx4 v[92:93], off
	s_waitcnt vmcnt(8)
	s_waitcnt lgkmcnt(0)
	s_barrier
	s_setprio 1
	v_mfma_f32_16x16x32_bf16 v[150:153], v[72:75], v[190:193], v[150:153]
	v_mfma_f32_16x16x32_bf16 v[146:149], v[80:83], v[190:193], v[146:149]
	v_mfma_f32_16x16x32_bf16 v[118:121], v[72:75], v[198:201], v[118:121]
	v_mfma_f32_16x16x32_bf16 v[114:117], v[80:83], v[198:201], v[114:117]
	v_mfma_f32_16x16x32_bf16 v[142:145], v[72:75], v[206:209], v[142:145]
	v_mfma_f32_16x16x32_bf16 v[134:137], v[80:83], v[206:209], v[134:137]
	v_mfma_f32_16x16x32_bf16 v[126:129], v[72:75], v[214:217], v[126:129]
	v_mfma_f32_16x16x32_bf16 v[122:125], v[80:83], v[214:217], v[122:125]
	v_mfma_f32_16x16x32_bf16 v[150:153], v[76:79], v[194:197], v[150:153]
	v_mfma_f32_16x16x32_bf16 v[146:149], v[84:87], v[194:197], v[146:149]
	v_mfma_f32_16x16x32_bf16 v[118:121], v[76:79], v[202:205], v[118:121]
	v_mfma_f32_16x16x32_bf16 v[114:117], v[84:87], v[202:205], v[114:117]
	v_mfma_f32_16x16x32_bf16 v[142:145], v[76:79], v[210:213], v[142:145]
	v_mfma_f32_16x16x32_bf16 v[134:137], v[84:87], v[210:213], v[134:137]
	v_mfma_f32_16x16x32_bf16 v[126:129], v[76:79], v[236:239], v[126:129]
	v_mfma_f32_16x16x32_bf16 v[122:125], v[84:87], v[236:239], v[122:125]
	v_mfma_f32_16x16x32_bf16 v[138:141], v[154:157], v[190:193], v[138:141]
	v_mfma_f32_16x16x32_bf16 v[130:133], v[182:185], v[190:193], v[130:133]
	v_mfma_f32_16x16x32_bf16 v[110:113], v[154:157], v[198:201], v[110:113]
	v_mfma_f32_16x16x32_bf16 v[106:109], v[182:185], v[198:201], v[106:109]
	v_mfma_f32_16x16x32_bf16 v[102:105], v[154:157], v[206:209], v[102:105]
	v_mfma_f32_16x16x32_bf16 v[98:101], v[182:185], v[206:209], v[98:101]
	v_mfma_f32_16x16x32_bf16 v[92:95], v[154:157], v[214:217], v[94:97]
	v_mfma_f32_16x16x32_bf16 v[88:91], v[182:185], v[214:217], v[88:91]
	v_mfma_f32_16x16x32_bf16 v[138:141], v[158:161], v[194:197], v[138:141]
	v_mfma_f32_16x16x32_bf16 v[130:133], v[186:189], v[194:197], v[130:133]
	v_mfma_f32_16x16x32_bf16 v[110:113], v[158:161], v[202:205], v[110:113]
	v_mfma_f32_16x16x32_bf16 v[106:109], v[186:189], v[202:205], v[106:109]
	v_mfma_f32_16x16x32_bf16 v[102:105], v[158:161], v[210:213], v[102:105]
	v_mfma_f32_16x16x32_bf16 v[98:101], v[186:189], v[210:213], v[98:101]
	v_mfma_f32_16x16x32_bf16 v[94:97], v[158:161], v[236:239], v[92:95]
	v_mfma_f32_16x16x32_bf16 v[90:93], v[186:189], v[236:239], v[88:91]
	s_setprio 0
	s_barrier
	s_add_i32 s38, s93, s55
	v_lshl_add_u64 v[88:89], v[220:221], 0, s[96:97]
	s_mov_b32 m0, s38
	ds_read_b128 v[190:193], v230 offset:49152
	ds_read_b128 v[194:197], v230 offset:50176
	ds_read_b128 v[198:201], v230 offset:51200
	ds_read_b128 v[202:205], v230 offset:52224
	ds_read_b128 v[206:209], v230 offset:53248
	ds_read_b128 v[210:213], v230 offset:54272
	ds_read_b128 v[214:217], v230 offset:55296
	ds_read_b128 v[236:239], v230 offset:56320
	global_load_lds_dwordx4 v[88:89], off
	s_add_i32 m0, s38, 0x2000
	s_add_u32 s38, s46, 0x80080
	v_lshl_add_u64 v[88:89], v[240:241], 0, s[96:97]
	s_addc_u32 s39, s47, 0
	s_add_i32 s46, s94, s55
	global_load_lds_dwordx4 v[88:89], off
	v_lshl_add_u64 v[88:89], s[38:39], 0, v[166:167]
	s_mov_b32 m0, s46
	s_nop 0
	global_load_lds_dwordx4 v[88:89], off
	v_lshl_add_u64 v[88:89], s[38:39], 0, v[162:163]
	s_add_i32 m0, s46, 0x2000
	s_nop 0
	global_load_lds_dwordx4 v[88:89], off
	v_lshl_add_u64 v[88:89], v[242:243], 0, s[96:97]
	s_mov_b32 m0, s75
	s_nop 0
	global_load_lds_dwordx4 v[88:89], off
	v_lshl_add_u64 v[88:89], v[244:245], 0, s[96:97]
	s_mov_b32 m0, s76
	s_nop 0
	global_load_lds_dwordx4 v[88:89], off
	s_waitcnt vmcnt(8)
	s_waitcnt lgkmcnt(0)
	s_barrier
	s_setprio 1
	v_mfma_f32_16x16x32_bf16 v[62:65], v[72:75], v[190:193], v[62:65]
	v_mfma_f32_16x16x32_bf16 v[58:61], v[80:83], v[190:193], v[58:61]
	v_mfma_f32_16x16x32_bf16 v[54:57], v[72:75], v[198:201], v[54:57]
	v_mfma_f32_16x16x32_bf16 v[46:49], v[80:83], v[198:201], v[46:49]
	v_mfma_f32_16x16x32_bf16 v[38:41], v[72:75], v[206:209], v[38:41]
	v_mfma_f32_16x16x32_bf16 v[30:33], v[80:83], v[206:209], v[30:33]
	v_mfma_f32_16x16x32_bf16 v[22:25], v[72:75], v[214:217], v[22:25]
	v_mfma_f32_16x16x32_bf16 v[14:17], v[80:83], v[214:217], v[14:17]
	v_mfma_f32_16x16x32_bf16 v[62:65], v[76:79], v[194:197], v[62:65]
	v_mfma_f32_16x16x32_bf16 v[58:61], v[84:87], v[194:197], v[58:61]
	v_mfma_f32_16x16x32_bf16 v[54:57], v[76:79], v[202:205], v[54:57]
	v_mfma_f32_16x16x32_bf16 v[46:49], v[84:87], v[202:205], v[46:49]
	v_mfma_f32_16x16x32_bf16 v[38:41], v[76:79], v[210:213], v[38:41]
	v_mfma_f32_16x16x32_bf16 v[30:33], v[84:87], v[210:213], v[30:33]
	v_mfma_f32_16x16x32_bf16 v[22:25], v[76:79], v[236:239], v[22:25]
	v_mfma_f32_16x16x32_bf16 v[14:17], v[84:87], v[236:239], v[14:17]
	v_mfma_f32_16x16x32_bf16 v[50:53], v[154:157], v[190:193], v[50:53]
	v_mfma_f32_16x16x32_bf16 v[42:45], v[182:185], v[190:193], v[42:45]
	v_mfma_f32_16x16x32_bf16 v[34:37], v[154:157], v[198:201], v[34:37]
	v_mfma_f32_16x16x32_bf16 v[26:29], v[182:185], v[198:201], v[26:29]
	v_mfma_f32_16x16x32_bf16 v[18:21], v[154:157], v[206:209], v[18:21]
	v_mfma_f32_16x16x32_bf16 v[10:13], v[182:185], v[206:209], v[10:13]
	v_mfma_f32_16x16x32_bf16 v[6:9], v[154:157], v[214:217], v[6:9]
	v_mfma_f32_16x16x32_bf16 v[2:5], v[182:185], v[214:217], v[2:5]
	v_mfma_f32_16x16x32_bf16 v[50:53], v[158:161], v[194:197], v[50:53]
	v_mfma_f32_16x16x32_bf16 v[42:45], v[186:189], v[194:197], v[42:45]
	v_mfma_f32_16x16x32_bf16 v[34:37], v[158:161], v[202:205], v[34:37]
	v_mfma_f32_16x16x32_bf16 v[26:29], v[186:189], v[202:205], v[26:29]
	v_mfma_f32_16x16x32_bf16 v[18:21], v[158:161], v[210:213], v[18:21]
	v_mfma_f32_16x16x32_bf16 v[10:13], v[186:189], v[210:213], v[10:13]
	v_mfma_f32_16x16x32_bf16 v[6:9], v[158:161], v[236:239], v[6:9]
	v_mfma_f32_16x16x32_bf16 v[2:5], v[186:189], v[236:239], v[2:5]
	s_setprio 0
	s_barrier
	s_add_i32 s91, s91, 2
	s_add_u32 s41, s41, 0x100
	s_addc_u32 s43, s43, 0
	s_cmp_gt_u32 s91, 29
	s_mov_b64 s[38:39], s[44:45]
	s_cbranch_scc1 .LBB0_755

.LBB0_904:
	s_add_u32 s19, s28, 0x100
	s_mov_b32 s98, 0
	s_addc_u32 s21, s29, 0
	s_mov_b32 s60, -2
.LBB0_905:
	s_add_u32 s8, s26, 0x100
	s_addc_u32 s9, s27, 0
	s_add_i32 s61, 0, 0x10000
	s_cmpk_eq_i32 s60, 0x54
	s_cselect_b32 s31, s23, s9
	s_cselect_b32 s30, s22, s8
	v_add_u32_e32 v0, s61, v212
	s_cselect_b32 s29, s25, s21
	s_cselect_b32 s28, s24, s19
	s_add_i32 s62, 0, 0x14000
	ds_read_b128 v[66:69], v0
	ds_read_b128 v[70:73], v0 offset:1024
	ds_read_b128 v[74:77], v0 offset:2048
	ds_read_b128 v[78:81], v0 offset:3072
	v_add_u32_e32 v0, s62, v212
	ds_read_b128 v[130:133], v0
	ds_read_b128 v[142:145], v0 offset:1024
	ds_read_b128 v[146:149], v0 offset:2048
	ds_read_b128 v[158:161], v0 offset:3072
	v_lshl_add_u64 v[220:221], s[26:27], 0, v[190:191]
	s_add_i32 m0, s39, 0xc000
	ds_read_b128 v[162:165], v215
	ds_read_b128 v[166:169], v215 offset:1024
	ds_read_b128 v[170:173], v215 offset:2048
	ds_read_b128 v[192:195], v215 offset:3072
	ds_read_b128 v[196:199], v215 offset:4096
	ds_read_b128 v[200:203], v215 offset:5120
	ds_read_b128 v[204:207], v215 offset:6144
	ds_read_b128 v[208:211], v215 offset:7168
	s_cmp_lg_u32 s98, 0
	s_cbranch_scc1 .Lzc_ph9_a
	v_mov_b64_e32 v[82:83], 0
	v_mov_b64_e32 v[84:85], 0
	v_mov_b64_e32 v[86:87], 0
	v_mov_b64_e32 v[88:89], 0
	v_mov_b64_e32 v[90:91], 0
	v_mov_b64_e32 v[92:93], 0
	v_mov_b64_e32 v[94:95], 0
	v_mov_b64_e32 v[96:97], 0
	v_mov_b64_e32 v[98:99], 0
	v_mov_b64_e32 v[100:101], 0
	v_mov_b64_e32 v[102:103], 0
	v_mov_b64_e32 v[104:105], 0
	v_mov_b64_e32 v[106:107], 0
	v_mov_b64_e32 v[108:109], 0
	v_mov_b64_e32 v[110:111], 0
	v_mov_b64_e32 v[112:113], 0
	v_mov_b64_e32 v[114:115], 0
	v_mov_b64_e32 v[116:117], 0
	v_mov_b64_e32 v[118:119], 0
	v_mov_b64_e32 v[120:121], 0
	v_mov_b64_e32 v[122:123], 0
	v_mov_b64_e32 v[124:125], 0
	v_mov_b64_e32 v[126:127], 0
	v_mov_b64_e32 v[128:129], 0
	v_mov_b64_e32 v[134:135], 0
	v_mov_b64_e32 v[136:137], 0
	v_mov_b64_e32 v[138:139], 0
	v_mov_b64_e32 v[140:141], 0
	v_mov_b64_e32 v[150:151], 0
	v_mov_b64_e32 v[152:153], 0
	v_mov_b64_e32 v[154:155], 0
	v_mov_b64_e32 v[156:157], 0
.Lzc_ph9_a:
	global_load_lds_dwordx4 v[220:221], off
	v_lshl_add_u64 v[220:221], s[26:27], 0, v[188:189]
	s_add_i32 m0, s39, 0xe000
	s_nop 0
	global_load_lds_dwordx4 v[220:221], off
	s_waitcnt vmcnt(8)
	s_waitcnt lgkmcnt(0)
	s_barrier
	s_setprio 1
	v_mfma_f32_16x16x32_bf16 v[154:157], v[66:69], v[162:165], v[154:157]
	v_mfma_f32_16x16x32_bf16 v[150:153], v[74:77], v[162:165], v[150:153]
	v_mfma_f32_16x16x32_bf16 v[138:141], v[66:69], v[170:173], v[138:141]
	v_mfma_f32_16x16x32_bf16 v[134:137], v[74:77], v[170:173], v[134:137]
	v_mfma_f32_16x16x32_bf16 v[110:113], v[66:69], v[196:199], v[110:113]
	v_mfma_f32_16x16x32_bf16 v[106:109], v[74:77], v[196:199], v[106:109]
	v_mfma_f32_16x16x32_bf16 v[94:97], v[66:69], v[204:207], v[94:97]
	v_mfma_f32_16x16x32_bf16 v[90:93], v[74:77], v[204:207], v[90:93]
	v_mfma_f32_16x16x32_bf16 v[154:157], v[70:73], v[166:169], v[154:157]
	v_mfma_f32_16x16x32_bf16 v[150:153], v[78:81], v[166:169], v[150:153]
	v_mfma_f32_16x16x32_bf16 v[138:141], v[70:73], v[192:195], v[138:141]
	v_mfma_f32_16x16x32_bf16 v[134:137], v[78:81], v[192:195], v[134:137]
	v_mfma_f32_16x16x32_bf16 v[110:113], v[70:73], v[200:203], v[110:113]
	v_mfma_f32_16x16x32_bf16 v[106:109], v[78:81], v[200:203], v[106:109]
	v_mfma_f32_16x16x32_bf16 v[94:97], v[70:73], v[208:211], v[94:97]
	v_mfma_f32_16x16x32_bf16 v[90:93], v[78:81], v[208:211], v[90:93]
	v_mfma_f32_16x16x32_bf16 v[126:129], v[130:133], v[162:165], v[126:129]
	v_mfma_f32_16x16x32_bf16 v[114:117], v[146:149], v[162:165], v[114:117]
	v_mfma_f32_16x16x32_bf16 v[122:125], v[130:133], v[170:173], v[122:125]
	v_mfma_f32_16x16x32_bf16 v[118:121], v[146:149], v[170:173], v[118:121]
	v_mfma_f32_16x16x32_bf16 v[102:105], v[130:133], v[196:199], v[102:105]
	v_mfma_f32_16x16x32_bf16 v[98:101], v[146:149], v[196:199], v[98:101]
	v_mfma_f32_16x16x32_bf16 v[86:89], v[130:133], v[204:207], v[86:89]
	v_mfma_f32_16x16x32_bf16 v[82:85], v[146:149], v[204:207], v[82:85]
	v_mfma_f32_16x16x32_bf16 v[126:129], v[142:145], v[166:169], v[126:129]
	v_mfma_f32_16x16x32_bf16 v[114:117], v[158:161], v[166:169], v[114:117]
	v_mfma_f32_16x16x32_bf16 v[122:125], v[142:145], v[192:195], v[122:125]
	v_mfma_f32_16x16x32_bf16 v[118:121], v[158:161], v[192:195], v[118:121]
	v_mfma_f32_16x16x32_bf16 v[102:105], v[142:145], v[200:203], v[102:105]
	v_mfma_f32_16x16x32_bf16 v[98:101], v[158:161], v[200:203], v[98:101]
	v_mfma_f32_16x16x32_bf16 v[86:89], v[142:145], v[208:211], v[86:89]
	v_mfma_f32_16x16x32_bf16 v[82:85], v[158:161], v[208:211], v[82:85]
	s_setprio 0
	s_barrier
	s_add_i32 s26, s61, s38
	v_lshl_add_u64 v[220:221], s[28:29], 0, v[182:183]
	s_mov_b32 m0, s26
	ds_read_b128 v[162:165], v215 offset:16384
	ds_read_b128 v[166:169], v215 offset:17408
	ds_read_b128 v[170:173], v215 offset:18432
	ds_read_b128 v[192:195], v215 offset:19456
	ds_read_b128 v[196:199], v215 offset:20480
	ds_read_b128 v[200:203], v215 offset:21504
	ds_read_b128 v[204:207], v215 offset:22528
	ds_read_b128 v[208:211], v215 offset:23552
	s_cmp_lg_u32 s98, 0
	s_cbranch_scc1 .Lzc_ph9_b
	v_mov_b64_e32 v[2:3], 0
	v_mov_b64_e32 v[4:5], 0
	v_mov_b64_e32 v[6:7], 0
	v_mov_b64_e32 v[8:9], 0
	v_mov_b64_e32 v[10:11], 0
	v_mov_b64_e32 v[12:13], 0
	v_mov_b64_e32 v[14:15], 0
	v_mov_b64_e32 v[16:17], 0
	v_mov_b64_e32 v[18:19], 0
	v_mov_b64_e32 v[20:21], 0
	v_mov_b64_e32 v[22:23], 0
	v_mov_b64_e32 v[24:25], 0
	v_mov_b64_e32 v[26:27], 0
	v_mov_b64_e32 v[28:29], 0
	v_mov_b64_e32 v[30:31], 0
	v_mov_b64_e32 v[32:33], 0
	v_mov_b64_e32 v[34:35], 0
	v_mov_b64_e32 v[36:37], 0
	v_mov_b64_e32 v[38:39], 0
	v_mov_b64_e32 v[40:41], 0
	v_mov_b64_e32 v[42:43], 0
	v_mov_b64_e32 v[44:45], 0
	v_mov_b64_e32 v[46:47], 0
	v_mov_b64_e32 v[48:49], 0
	v_mov_b64_e32 v[50:51], 0
	v_mov_b64_e32 v[52:53], 0
	v_mov_b64_e32 v[54:55], 0
	v_mov_b64_e32 v[56:57], 0
	v_mov_b64_e32 v[58:59], 0
	v_mov_b64_e32 v[60:61], 0
	v_mov_b64_e32 v[62:63], 0
	v_mov_b64_e32 v[64:65], 0
	s_mov_b32 s98, 1
.Lzc_ph9_b:
	global_load_lds_dwordx4 v[220:221], off
	s_add_i32 m0, s26, 0x2000
	s_add_u32 s26, s28, 0x160000
	v_lshl_add_u64 v[230:231], s[28:29], 0, v[178:179]
	s_addc_u32 s27, s29, 0
	s_add_i32 s61, s62, s38
	global_load_lds_dwordx4 v[230:231], off
	v_lshl_add_u64 v[232:233], s[26:27], 0, v[182:183]
	s_mov_b32 m0, s61
	v_lshl_add_u64 v[234:235], s[30:31], 0, v[180:181]
	global_load_lds_dwordx4 v[232:233], off
	v_lshl_add_u64 v[232:233], s[26:27], 0, v[178:179]
	s_add_i32 m0, s61, 0x2000
	s_nop 0
	global_load_lds_dwordx4 v[232:233], off
	v_lshl_add_u64 v[232:233], s[30:31], 0, v[184:185]
	s_mov_b32 m0, s39
	s_nop 0
	global_load_lds_dwordx4 v[232:233], off
	s_mov_b32 m0, s40
	s_nop 0
	global_load_lds_dwordx4 v[234:235], off
	s_waitcnt vmcnt(8)
	s_waitcnt lgkmcnt(0)
	s_barrier
	s_setprio 1
	v_mfma_f32_16x16x32_bf16 v[62:65], v[66:69], v[162:165], v[62:65]
	v_mfma_f32_16x16x32_bf16 v[58:61], v[74:77], v[162:165], v[58:61]
	v_mfma_f32_16x16x32_bf16 v[46:49], v[66:69], v[170:173], v[46:49]
	v_mfma_f32_16x16x32_bf16 v[42:45], v[74:77], v[170:173], v[42:45]
	v_mfma_f32_16x16x32_bf16 v[30:33], v[66:69], v[196:199], v[30:33]
	v_mfma_f32_16x16x32_bf16 v[26:29], v[74:77], v[196:199], v[26:29]
	v_mfma_f32_16x16x32_bf16 v[14:17], v[66:69], v[204:207], v[14:17]
	v_mfma_f32_16x16x32_bf16 v[10:13], v[74:77], v[204:207], v[10:13]
	v_mfma_f32_16x16x32_bf16 v[62:65], v[70:73], v[166:169], v[62:65]
	v_mfma_f32_16x16x32_bf16 v[58:61], v[78:81], v[166:169], v[58:61]
	v_mfma_f32_16x16x32_bf16 v[46:49], v[70:73], v[192:195], v[46:49]
	v_mfma_f32_16x16x32_bf16 v[42:45], v[78:81], v[192:195], v[42:45]
	v_mfma_f32_16x16x32_bf16 v[30:33], v[70:73], v[200:203], v[30:33]
	v_mfma_f32_16x16x32_bf16 v[26:29], v[78:81], v[200:203], v[26:29]
	v_mfma_f32_16x16x32_bf16 v[14:17], v[70:73], v[208:211], v[14:17]
	v_mfma_f32_16x16x32_bf16 v[10:13], v[78:81], v[208:211], v[10:13]
	v_mfma_f32_16x16x32_bf16 v[54:57], v[130:133], v[162:165], v[54:57]
	v_mfma_f32_16x16x32_bf16 v[50:53], v[146:149], v[162:165], v[50:53]
	v_mfma_f32_16x16x32_bf16 v[38:41], v[130:133], v[170:173], v[38:41]
	v_mfma_f32_16x16x32_bf16 v[34:37], v[146:149], v[170:173], v[34:37]
	v_mfma_f32_16x16x32_bf16 v[22:25], v[130:133], v[196:199], v[22:25]
	v_mfma_f32_16x16x32_bf16 v[18:21], v[146:149], v[196:199], v[18:21]
	v_mfma_f32_16x16x32_bf16 v[6:9], v[130:133], v[204:207], v[6:9]
	v_mfma_f32_16x16x32_bf16 v[2:5], v[146:149], v[204:207], v[2:5]
	v_mfma_f32_16x16x32_bf16 v[54:57], v[142:145], v[166:169], v[54:57]
	v_mfma_f32_16x16x32_bf16 v[50:53], v[158:161], v[166:169], v[50:53]
	v_mfma_f32_16x16x32_bf16 v[38:41], v[142:145], v[192:195], v[38:41]
	v_mfma_f32_16x16x32_bf16 v[34:37], v[158:161], v[192:195], v[34:37]
	v_mfma_f32_16x16x32_bf16 v[22:25], v[142:145], v[200:203], v[22:25]
	v_mfma_f32_16x16x32_bf16 v[18:21], v[158:161], v[200:203], v[18:21]
	v_mfma_f32_16x16x32_bf16 v[6:9], v[142:145], v[208:211], v[6:9]
	v_mfma_f32_16x16x32_bf16 v[2:5], v[158:161], v[208:211], v[2:5]
	s_setprio 0
	s_barrier
	s_add_i32 s61, 0, 0x18000
	v_add_u32_e32 v0, s61, v212
	s_add_i32 s62, 0, 0x1c000
	ds_read_b128 v[66:69], v0
	ds_read_b128 v[70:73], v0 offset:1024
	ds_read_b128 v[74:77], v0 offset:2048
	ds_read_b128 v[78:81], v0 offset:3072
	v_add_u32_e32 v0, s62, v212
	ds_read_b128 v[130:133], v0
	ds_read_b128 v[142:145], v0 offset:1024
	ds_read_b128 v[146:149], v0 offset:2048
	ds_read_b128 v[158:161], v0 offset:3072
	s_add_u32 s26, s30, 0x160000
	s_addc_u32 s27, s31, 0
	s_mov_b32 m0, s41
	v_lshl_add_u64 v[236:237], s[26:27], 0, v[184:185]
	ds_read_b128 v[162:165], v215 offset:32768
	ds_read_b128 v[166:169], v215 offset:33792
	ds_read_b128 v[170:173], v215 offset:34816
	ds_read_b128 v[192:195], v215 offset:35840
	ds_read_b128 v[196:199], v215 offset:36864
	ds_read_b128 v[200:203], v215 offset:37888
	ds_read_b128 v[204:207], v215 offset:38912
	ds_read_b128 v[208:211], v215 offset:39936
	global_load_lds_dwordx4 v[236:237], off
	v_lshl_add_u64 v[236:237], s[26:27], 0, v[180:181]
	s_mov_b32 m0, s42
	s_nop 0
	global_load_lds_dwordx4 v[236:237], off
	s_waitcnt vmcnt(8)
	s_waitcnt lgkmcnt(0)
	s_barrier
	s_setprio 1
	v_mfma_f32_16x16x32_bf16 v[154:157], v[66:69], v[162:165], v[154:157]
	v_mfma_f32_16x16x32_bf16 v[150:153], v[74:77], v[162:165], v[150:153]
	v_mfma_f32_16x16x32_bf16 v[138:141], v[66:69], v[170:173], v[138:141]
	v_mfma_f32_16x16x32_bf16 v[134:137], v[74:77], v[170:173], v[134:137]
	v_mfma_f32_16x16x32_bf16 v[110:113], v[66:69], v[196:199], v[110:113]
	v_mfma_f32_16x16x32_bf16 v[106:109], v[74:77], v[196:199], v[106:109]
	v_mfma_f32_16x16x32_bf16 v[94:97], v[66:69], v[204:207], v[94:97]
	v_mfma_f32_16x16x32_bf16 v[90:93], v[74:77], v[204:207], v[90:93]
	v_mfma_f32_16x16x32_bf16 v[154:157], v[70:73], v[166:169], v[154:157]
	v_mfma_f32_16x16x32_bf16 v[150:153], v[78:81], v[166:169], v[150:153]
	v_mfma_f32_16x16x32_bf16 v[138:141], v[70:73], v[192:195], v[138:141]
	v_mfma_f32_16x16x32_bf16 v[134:137], v[78:81], v[192:195], v[134:137]
	v_mfma_f32_16x16x32_bf16 v[110:113], v[70:73], v[200:203], v[110:113]
	v_mfma_f32_16x16x32_bf16 v[106:109], v[78:81], v[200:203], v[106:109]
	v_mfma_f32_16x16x32_bf16 v[94:97], v[70:73], v[208:211], v[94:97]
	v_mfma_f32_16x16x32_bf16 v[90:93], v[78:81], v[208:211], v[90:93]
	v_mfma_f32_16x16x32_bf16 v[126:129], v[130:133], v[162:165], v[126:129]
	v_mfma_f32_16x16x32_bf16 v[114:117], v[146:149], v[162:165], v[114:117]
	v_mfma_f32_16x16x32_bf16 v[122:125], v[130:133], v[170:173], v[122:125]
	v_mfma_f32_16x16x32_bf16 v[118:121], v[146:149], v[170:173], v[118:121]
	v_mfma_f32_16x16x32_bf16 v[102:105], v[130:133], v[196:199], v[102:105]
	v_mfma_f32_16x16x32_bf16 v[98:101], v[146:149], v[196:199], v[98:101]
	v_mfma_f32_16x16x32_bf16 v[86:89], v[130:133], v[204:207], v[86:89]
	v_mfma_f32_16x16x32_bf16 v[82:85], v[146:149], v[204:207], v[82:85]
	v_mfma_f32_16x16x32_bf16 v[126:129], v[142:145], v[166:169], v[126:129]
	v_mfma_f32_16x16x32_bf16 v[114:117], v[158:161], v[166:169], v[114:117]
	v_mfma_f32_16x16x32_bf16 v[122:125], v[142:145], v[192:195], v[122:125]
	v_mfma_f32_16x16x32_bf16 v[118:121], v[158:161], v[192:195], v[118:121]
	v_mfma_f32_16x16x32_bf16 v[102:105], v[142:145], v[200:203], v[102:105]
	v_mfma_f32_16x16x32_bf16 v[98:101], v[158:161], v[200:203], v[98:101]
	v_mfma_f32_16x16x32_bf16 v[86:89], v[142:145], v[208:211], v[86:89]
	v_mfma_f32_16x16x32_bf16 v[82:85], v[158:161], v[208:211], v[82:85]
	s_setprio 0
	s_barrier
	s_add_i32 s26, s61, s38
	v_lshl_add_u64 v[220:221], v[220:221], 0, s[96:97]
	s_mov_b32 m0, s26
	ds_read_b128 v[162:165], v215 offset:49152
	ds_read_b128 v[166:169], v215 offset:50176
	ds_read_b128 v[170:173], v215 offset:51200
	ds_read_b128 v[192:195], v215 offset:52224
	ds_read_b128 v[196:199], v215 offset:53248
	ds_read_b128 v[200:203], v215 offset:54272
	ds_read_b128 v[204:207], v215 offset:55296
	ds_read_b128 v[208:211], v215 offset:56320
	global_load_lds_dwordx4 v[220:221], off
	s_add_i32 m0, s26, 0x2000
	s_add_u32 s26, s28, 0x160080
	v_lshl_add_u64 v[220:221], v[230:231], 0, s[96:97]
	s_addc_u32 s27, s29, 0
	s_add_i32 s28, s62, s38
	global_load_lds_dwordx4 v[220:221], off
	v_lshl_add_u64 v[220:221], s[26:27], 0, v[182:183]
	s_mov_b32 m0, s28
	s_nop 0
	global_load_lds_dwordx4 v[220:221], off
	v_lshl_add_u64 v[220:221], s[26:27], 0, v[178:179]
	s_add_i32 m0, s28, 0x2000
	s_nop 0
	global_load_lds_dwordx4 v[220:221], off
	v_lshl_add_u64 v[220:221], v[232:233], 0, s[96:97]
	s_mov_b32 m0, s54
	s_nop 0
	global_load_lds_dwordx4 v[220:221], off
	v_lshl_add_u64 v[220:221], v[234:235], 0, s[96:97]
	s_mov_b32 m0, s55
	s_nop 0
	global_load_lds_dwordx4 v[220:221], off
	s_waitcnt vmcnt(8)
	s_waitcnt lgkmcnt(0)
	s_barrier
	s_setprio 1
	v_mfma_f32_16x16x32_bf16 v[62:65], v[66:69], v[162:165], v[62:65]
	v_mfma_f32_16x16x32_bf16 v[58:61], v[74:77], v[162:165], v[58:61]
	v_mfma_f32_16x16x32_bf16 v[46:49], v[66:69], v[170:173], v[46:49]
	v_mfma_f32_16x16x32_bf16 v[42:45], v[74:77], v[170:173], v[42:45]
	v_mfma_f32_16x16x32_bf16 v[30:33], v[66:69], v[196:199], v[30:33]
	v_mfma_f32_16x16x32_bf16 v[26:29], v[74:77], v[196:199], v[26:29]
	v_mfma_f32_16x16x32_bf16 v[14:17], v[66:69], v[204:207], v[14:17]
	v_mfma_f32_16x16x32_bf16 v[10:13], v[74:77], v[204:207], v[10:13]
	v_mfma_f32_16x16x32_bf16 v[62:65], v[70:73], v[166:169], v[62:65]
	v_mfma_f32_16x16x32_bf16 v[58:61], v[78:81], v[166:169], v[58:61]
	v_mfma_f32_16x16x32_bf16 v[46:49], v[70:73], v[192:195], v[46:49]
	v_mfma_f32_16x16x32_bf16 v[42:45], v[78:81], v[192:195], v[42:45]
	v_mfma_f32_16x16x32_bf16 v[30:33], v[70:73], v[200:203], v[30:33]
	v_mfma_f32_16x16x32_bf16 v[26:29], v[78:81], v[200:203], v[26:29]
	v_mfma_f32_16x16x32_bf16 v[14:17], v[70:73], v[208:211], v[14:17]
	v_mfma_f32_16x16x32_bf16 v[10:13], v[78:81], v[208:211], v[10:13]
	v_mfma_f32_16x16x32_bf16 v[54:57], v[130:133], v[162:165], v[54:57]
	v_mfma_f32_16x16x32_bf16 v[50:53], v[146:149], v[162:165], v[50:53]
	v_mfma_f32_16x16x32_bf16 v[38:41], v[130:133], v[170:173], v[38:41]
	v_mfma_f32_16x16x32_bf16 v[34:37], v[146:149], v[170:173], v[34:37]
	v_mfma_f32_16x16x32_bf16 v[22:25], v[130:133], v[196:199], v[22:25]
	v_mfma_f32_16x16x32_bf16 v[18:21], v[146:149], v[196:199], v[18:21]
	v_mfma_f32_16x16x32_bf16 v[6:9], v[130:133], v[204:207], v[6:9]
	v_mfma_f32_16x16x32_bf16 v[2:5], v[146:149], v[204:207], v[2:5]
	v_mfma_f32_16x16x32_bf16 v[54:57], v[142:145], v[166:169], v[54:57]
	v_mfma_f32_16x16x32_bf16 v[50:53], v[158:161], v[166:169], v[50:53]
	v_mfma_f32_16x16x32_bf16 v[38:41], v[142:145], v[192:195], v[38:41]
	v_mfma_f32_16x16x32_bf16 v[34:37], v[158:161], v[192:195], v[34:37]
	v_mfma_f32_16x16x32_bf16 v[22:25], v[142:145], v[200:203], v[22:25]
	v_mfma_f32_16x16x32_bf16 v[18:21], v[158:161], v[200:203], v[18:21]
	v_mfma_f32_16x16x32_bf16 v[6:9], v[142:145], v[208:211], v[6:9]
	v_mfma_f32_16x16x32_bf16 v[2:5], v[158:161], v[208:211], v[2:5]
	s_setprio 0
	s_barrier
	s_add_i32 s60, s60, 2
	s_add_u32 s19, s19, 0x100
	s_addc_u32 s21, s21, 0
	s_cmpk_gt_u32 s60, 0x55
	s_mov_b64 s[26:27], s[8:9]
	s_cbranch_scc0 .LBB0_905
	s_and_b64 vcc, exec, s[16:17]
	s_cbranch_vccz .LBB0_908
	s_barrier
